# P3 scan: the two LDS waits of each token merged into one (stricter count at the token's first instruction)
# baseline (speedup 1.0000x reference)
; #define LAS __attribute__((address_space(3)))
; __device__ __forceinline__ void rwkv_scan_prompt(const Params& p, LAS unsigned char* lds, int bh, int rq) {
;     ...
;             const LAS float* ob = OPS + buf * TC * 6 * 64;
;             f32x4 r4 = *(const LAS f32x4*)(ob + cg_ * 4), d4 = *(const LAS f32x4*)(ob + 64 + cg_ * 4), k4 = *(const LAS f32x4*)(ob + 128 + cg_ * 4),
;                   a4 = *(const LAS f32x4*)(ob + 256 + cg_ * 4), b4 = *(const LAS f32x4*)(ob + 320 + cg_ * 4);
;             float vv = ob[192 + rq * 16 + rloc];
;             f32x4 rp = r4;
; #pragma unroll
;             for (int tk = 0; tk < TC; ++tk) {
;                 f32x4 nr4 = r4, nd4 = d4, nk4 = k4, na4 = a4, nb4 = b4; float nvv = vv;
;                 if (tk < TC - 1) {
;                     const LAS float* o = ob + (tk + 1) * 6 * 64;
;                     nr4 = *(const LAS f32x4*)(o + cg_ * 4); nd4 = *(const LAS f32x4*)(o + 64 + cg_ * 4); nk4 = *(const LAS f32x4*)(o + 128 + cg_ * 4);
;                     na4 = *(const LAS f32x4*)(o + 256 + cg_ * 4); nb4 = *(const LAS f32x4*)(o + 320 + cg_ * 4);
;                     nvv = o[192 + rq * 16 + rloc];
;                 }
;                 __builtin_amdgcn_sched_barrier(0);
;                 typedef float f32x2_ __attribute__((ext_vector_type(2)));
;                 f32x2_ ta = (f32x2_){S[0], S[1]} * (f32x2_){a4[0], a4[1]}; ta = (f32x2_){S[2], S[3]} * (f32x2_){a4[2], a4[3]} + ta;
;                 f32x2_ ty = (f32x2_){S[0], S[1]} * (f32x2_){rp[0], rp[1]}; ty = (f32x2_){S[2], S[3]} * (f32x2_){rp[2], rp[3]} + ty;
;                 const f32x4 T = S * d4 + vv * k4;
;                 float sa = ta[0] + ta[1];
;                 float yp = ty[0] + ty[1];
;                 sa = dpp_add<0xB1>(sa); yp = dpp_add<0xB1>(yp);
;                 sa = dpp_add<0x4E>(sa); yp = dpp_add<0x4E>(yp);
;                 sa = dpp_add<0x124>(sa); yp = dpp_add<0x124>(yp);
;                 sa = dpp_add<0x128>(sa); yp = dpp_add<0x128>(yp);
;                 if (tk > 0) yk[(tk - 1) >> 4] = (cg_ == ((tk - 1) & 15)) ? yp : yk[(tk - 1) >> 4];
;                 S = sa * b4 + T;
;                 rp = r4;
;                 r4 = nr4; d4 = nd4; k4 = nk4; a4 = na4; b4 = nb4; vv = nvv;
.LBB0_336:
	s_and_b32 s95, s73, 1
	s_and_saveexec_b64 s[74:75], s[38:39]
	s_xor_b64 s[74:75], exec, s[74:75]
	s_cbranch_execz .LBB0_338
	s_mul_i32 s78, s95, 0xc000
	s_add_i32 s78, s78, 0
	v_lshl_add_u32 v28, v36, 2, s78
	v_lshl_add_u32 v29, v154, 2, s78
	ds_read_b128 v[30:33], v28
	ds_read_b128 v[160:163], v28 offset:256
	ds_read_b128 v[164:167], v28 offset:512
	ds_read_b128 v[168:171], v28 offset:1024
	ds_read2st64_b32 v[34:35], v29 offset0:3 offset1:9
	ds_read_b128 v[172:175], v28 offset:1280
	ds_read_b128 v[176:179], v28 offset:1536
	ds_read_b128 v[180:183], v28 offset:1792
	ds_read_b128 v[184:187], v28 offset:2048
	ds_read_b128 v[188:191], v28 offset:2560
	ds_read_b128 v[192:195], v28 offset:2816
	s_waitcnt lgkmcnt(7)
	v_pk_mul_f32 v[170:171], v[26:27], v[170:171]
	s_waitcnt lgkmcnt(6)
	v_pk_mul_f32 v[164:165], v[164:165], v[34:35] op_sel_hi:[1,0]
	v_pk_fma_f32 v[168:169], v[24:25], v[168:169], v[170:171]
	v_pk_mul_f32 v[166:167], v[166:167], v[34:35] op_sel_hi:[1,0]
	v_add_f32_e32 v168, v168, v169
	v_pk_fma_f32 v[26:27], v[26:27], v[162:163], v[166:167]
	v_pk_fma_f32 v[24:25], v[24:25], v[160:161], v[164:165]
	v_add_f32_dpp v168, v168, v168 quad_perm:[1,0,3,2] row_mask:0xf bank_mask:0xf bound_ctrl:1
	s_nop 1
	v_add_f32_dpp v168, v168, v168 quad_perm:[2,3,0,1] row_mask:0xf bank_mask:0xf bound_ctrl:1
	s_nop 1
	v_add_f32_dpp v168, v168, v168 row_ror:4 row_mask:0xf bank_mask:0xf bound_ctrl:1
	s_nop 1
	v_add_f32_dpp v168, v168, v168 row_ror:8 row_mask:0xf bank_mask:0xf bound_ctrl:1
	s_waitcnt lgkmcnt(5)
	v_pk_fma_f32 v[196:197], v[172:173], v[168:169], v[24:25] op_sel_hi:[1,0,1]
	v_pk_fma_f32 v[198:199], v[174:175], v[168:169], v[26:27] op_sel_hi:[1,0,1]
	ds_read_b128 v[24:27], v28 offset:3072
	ds_read_b128 v[160:163], v28 offset:3328
	ds_read_b128 v[164:167], v28 offset:3584
	ds_read_b128 v[168:171], v28 offset:4096
	ds_read_b128 v[172:175], v28 offset:4352
	ds_read_b32 v34, v29 offset:3840
	s_waitcnt lgkmcnt(6)
	v_pk_mul_f32 v[190:191], v[190:191], v[198:199]
	v_pk_mul_f32 v[32:33], v[32:33], v[198:199]
	v_pk_fma_f32 v[188:189], v[188:189], v[196:197], v[190:191]
	v_pk_fma_f32 v[30:31], v[30:31], v[196:197], v[32:33]
	v_pk_mul_f32 v[32:33], v[180:181], v[196:197]
	v_add_f32_e32 v206, v188, v189
	v_pk_mul_f32 v[180:181], v[182:183], v[198:199]
	v_add_f32_e32 v30, v30, v31
	v_add_f32_dpp v31, v206, v206 quad_perm:[1,0,3,2] row_mask:0xf bank_mask:0xf bound_ctrl:1
	v_mov_b32_e32 v182, v35
	v_add_f32_dpp v30, v30, v30 quad_perm:[1,0,3,2] row_mask:0xf bank_mask:0xf bound_ctrl:1
	v_add_f32_dpp v31, v31, v31 quad_perm:[2,3,0,1] row_mask:0xf bank_mask:0xf bound_ctrl:1
	v_pk_fma_f32 v[180:181], v[186:187], v[182:183], v[180:181] op_sel_hi:[1,0,1]
	v_add_f32_dpp v30, v30, v30 quad_perm:[2,3,0,1] row_mask:0xf bank_mask:0xf bound_ctrl:1
	v_add_f32_dpp v31, v31, v31 row_ror:4 row_mask:0xf bank_mask:0xf bound_ctrl:1
	v_pk_fma_f32 v[32:33], v[184:185], v[182:183], v[32:33] op_sel_hi:[1,0,1]
	v_add_f32_dpp v35, v30, v30 row_ror:4 row_mask:0xf bank_mask:0xf bound_ctrl:1
	v_add_f32_dpp v30, v31, v31 row_ror:8 row_mask:0xf bank_mask:0xf bound_ctrl:1
	v_pk_fma_f32 v[196:197], v[192:193], v[30:31], v[32:33] op_sel_hi:[1,0,1]
	v_add_f32_dpp v31, v35, v35 row_ror:8 row_mask:0xf bank_mask:0xf bound_ctrl:1
	v_cndmask_b32_e64 v201, 0, v31, s[6:7]
	v_pk_fma_f32 v[198:199], v[194:195], v[30:31], v[180:181] op_sel_hi:[1,0,1]
	ds_read_b128 v[30:33], v28 offset:4608
	ds_read_b128 v[180:183], v28 offset:4864
	ds_read_b128 v[184:187], v28 offset:5120
	ds_read_b128 v[188:191], v28 offset:5632
	ds_read_b128 v[192:195], v28 offset:5888
	ds_read_b32 v200, v29 offset:5376
	s_waitcnt lgkmcnt(6)
	v_pk_mul_f32 v[170:171], v[170:171], v[198:199]
	v_pk_mul_f32 v[160:161], v[160:161], v[196:197]
	v_pk_fma_f32 v[168:169], v[168:169], v[196:197], v[170:171]
	v_pk_mul_f32 v[170:171], v[178:179], v[198:199]
	v_pk_mul_f32 v[162:163], v[162:163], v[198:199]
	v_pk_fma_f32 v[170:171], v[176:177], v[196:197], v[170:171]
	v_pk_fma_f32 v[162:163], v[166:167], v[34:35], v[162:163] op_sel_hi:[1,0,1]
	v_add_f32_e32 v206, v168, v169
	v_pk_fma_f32 v[34:35], v[164:165], v[34:35], v[160:161] op_sel_hi:[1,0,1]
	v_add_f32_e32 v161, v170, v171
	v_add_f32_dpp v160, v206, v206 quad_perm:[1,0,3,2] row_mask:0xf bank_mask:0xf bound_ctrl:1
	s_nop 0
	v_add_f32_dpp v161, v161, v161 quad_perm:[1,0,3,2] row_mask:0xf bank_mask:0xf bound_ctrl:1
	v_add_f32_dpp v160, v160, v160 quad_perm:[2,3,0,1] row_mask:0xf bank_mask:0xf bound_ctrl:1
	s_nop 0
	v_add_f32_dpp v161, v161, v161 quad_perm:[2,3,0,1] row_mask:0xf bank_mask:0xf bound_ctrl:1
	v_add_f32_dpp v160, v160, v160 row_ror:4 row_mask:0xf bank_mask:0xf bound_ctrl:1
	s_nop 0
	v_add_f32_dpp v161, v161, v161 row_ror:4 row_mask:0xf bank_mask:0xf bound_ctrl:1
	v_add_f32_dpp v160, v160, v160 row_ror:8 row_mask:0xf bank_mask:0xf bound_ctrl:1
	v_pk_fma_f32 v[34:35], v[172:173], v[160:161], v[34:35] op_sel_hi:[1,0,1]
	v_add_f32_dpp v161, v161, v161 row_ror:8 row_mask:0xf bank_mask:0xf bound_ctrl:1
	v_cndmask_b32_e64 v199, v201, v161, s[8:9]
	v_pk_fma_f32 v[196:197], v[174:175], v[160:161], v[162:163] op_sel_hi:[1,0,1]
	ds_read_b128 v[160:163], v28 offset:6144
	ds_read_b128 v[164:167], v28 offset:6400
	ds_read_b128 v[168:171], v28 offset:6656
	ds_read_b128 v[172:175], v28 offset:7168
	ds_read_b128 v[176:179], v28 offset:7424
	ds_read_b32 v198, v29 offset:6912
	s_waitcnt lgkmcnt(6)
; #define LAS __attribute__((address_space(3)))
; __device__ __forceinline__ void rwkv_scan_prompt(const Params& p, LAS unsigned char* lds, int bh, int rq) {
;     ...
;             for (int tk = 0; tk < TC; ++tk) {
;                 f32x4 nr4 = r4, nd4 = d4, nk4 = k4, na4 = a4, nb4 = b4; float nvv = vv;
;                 if (tk < TC - 1) {
;                     const LAS float* o = ob + (tk + 1) * 6 * 64;
;                     nr4 = *(const LAS f32x4*)(o + cg_ * 4); nd4 = *(const LAS f32x4*)(o + 64 + cg_ * 4); nk4 = *(const LAS f32x4*)(o + 128 + cg_ * 4);
;                     na4 = *(const LAS f32x4*)(o + 256 + cg_ * 4); nb4 = *(const LAS f32x4*)(o + 320 + cg_ * 4);
;                     nvv = o[192 + rq * 16 + rloc];
;                 }
;                 __builtin_amdgcn_sched_barrier(0);
;                 typedef float f32x2_ __attribute__((ext_vector_type(2)));
;                 f32x2_ ta = (f32x2_){S[0], S[1]} * (f32x2_){a4[0], a4[1]}; ta = (f32x2_){S[2], S[3]} * (f32x2_){a4[2], a4[3]} + ta;
;                 f32x2_ ty = (f32x2_){S[0], S[1]} * (f32x2_){rp[0], rp[1]}; ty = (f32x2_){S[2], S[3]} * (f32x2_){rp[2], rp[3]} + ty;
;                 const f32x4 T = S * d4 + vv * k4;
;                 float sa = ta[0] + ta[1];
;                 float yp = ty[0] + ty[1];
;                 sa = dpp_add<0xB1>(sa); yp = dpp_add<0xB1>(yp);
;                 sa = dpp_add<0x4E>(sa); yp = dpp_add<0x4E>(yp);
;                 sa = dpp_add<0x124>(sa); yp = dpp_add<0x124>(yp);
;                 sa = dpp_add<0x128>(sa); yp = dpp_add<0x128>(yp);
;                 if (tk > 0) yk[(tk - 1) >> 4] = (cg_ == ((tk - 1) & 15)) ? yp : yk[(tk - 1) >> 4];
;                 S = sa * b4 + T;
;                 rp = r4;
;                 r4 = nr4; d4 = nd4; k4 = nk4; a4 = na4; b4 = nb4; vv = nvv;
	v_pk_mul_f32 v[190:191], v[190:191], v[196:197]
	v_pk_mul_f32 v[26:27], v[26:27], v[196:197]
	v_pk_fma_f32 v[188:189], v[188:189], v[34:35], v[190:191]
	v_pk_fma_f32 v[24:25], v[24:25], v[34:35], v[26:27]
	v_add_f32_e32 v206, v188, v189
	v_pk_mul_f32 v[26:27], v[180:181], v[34:35]
	v_add_f32_e32 v24, v24, v25
	v_add_f32_dpp v25, v206, v206 quad_perm:[1,0,3,2] row_mask:0xf bank_mask:0xf bound_ctrl:1
	v_pk_mul_f32 v[34:35], v[182:183], v[196:197]
	v_add_f32_dpp v24, v24, v24 quad_perm:[1,0,3,2] row_mask:0xf bank_mask:0xf bound_ctrl:1
	v_add_f32_dpp v25, v25, v25 quad_perm:[2,3,0,1] row_mask:0xf bank_mask:0xf bound_ctrl:1
	v_pk_fma_f32 v[34:35], v[186:187], v[200:201], v[34:35] op_sel_hi:[1,0,1]
	v_add_f32_dpp v24, v24, v24 quad_perm:[2,3,0,1] row_mask:0xf bank_mask:0xf bound_ctrl:1
	v_add_f32_dpp v25, v25, v25 row_ror:4 row_mask:0xf bank_mask:0xf bound_ctrl:1
	v_pk_fma_f32 v[26:27], v[184:185], v[200:201], v[26:27] op_sel_hi:[1,0,1]
	v_add_f32_dpp v180, v24, v24 row_ror:4 row_mask:0xf bank_mask:0xf bound_ctrl:1
	v_add_f32_dpp v24, v25, v25 row_ror:8 row_mask:0xf bank_mask:0xf bound_ctrl:1
	v_pk_fma_f32 v[196:197], v[192:193], v[24:25], v[26:27] op_sel_hi:[1,0,1]
	v_add_f32_dpp v25, v180, v180 row_ror:8 row_mask:0xf bank_mask:0xf bound_ctrl:1
	v_cndmask_b32_e64 v199, v199, v25, s[10:11]
	v_pk_fma_f32 v[34:35], v[194:195], v[24:25], v[34:35] op_sel_hi:[1,0,1]
	ds_read_b128 v[24:27], v28 offset:7680
	ds_read_b128 v[180:183], v28 offset:7936
	ds_read_b128 v[184:187], v28 offset:8192
	ds_read_b128 v[188:191], v28 offset:8704
	ds_read_b128 v[192:195], v28 offset:8960
	ds_read_b32 v200, v29 offset:8448
	s_waitcnt lgkmcnt(6)
	v_pk_mul_f32 v[174:175], v[174:175], v[34:35]
	v_pk_mul_f32 v[32:33], v[32:33], v[34:35]
	v_pk_fma_f32 v[172:173], v[172:173], v[196:197], v[174:175]
	v_pk_fma_f32 v[30:31], v[30:31], v[196:197], v[32:33]
	v_add_f32_e32 v206, v172, v173
	v_pk_mul_f32 v[32:33], v[164:165], v[196:197]
	v_add_f32_e32 v30, v30, v31
	v_add_f32_dpp v31, v206, v206 quad_perm:[1,0,3,2] row_mask:0xf bank_mask:0xf bound_ctrl:1
	v_pk_mul_f32 v[34:35], v[166:167], v[34:35]
	v_add_f32_dpp v30, v30, v30 quad_perm:[1,0,3,2] row_mask:0xf bank_mask:0xf bound_ctrl:1
	v_add_f32_dpp v31, v31, v31 quad_perm:[2,3,0,1] row_mask:0xf bank_mask:0xf bound_ctrl:1
	v_pk_fma_f32 v[34:35], v[170:171], v[198:199], v[34:35] op_sel_hi:[1,0,1]
	v_add_f32_dpp v30, v30, v30 quad_perm:[2,3,0,1] row_mask:0xf bank_mask:0xf bound_ctrl:1
	v_add_f32_dpp v31, v31, v31 row_ror:4 row_mask:0xf bank_mask:0xf bound_ctrl:1
	v_pk_fma_f32 v[32:33], v[168:169], v[198:199], v[32:33] op_sel_hi:[1,0,1]
	v_add_f32_dpp v164, v30, v30 row_ror:4 row_mask:0xf bank_mask:0xf bound_ctrl:1
	v_add_f32_dpp v30, v31, v31 row_ror:8 row_mask:0xf bank_mask:0xf bound_ctrl:1
	v_pk_fma_f32 v[196:197], v[176:177], v[30:31], v[32:33] op_sel_hi:[1,0,1]
	v_add_f32_dpp v31, v164, v164 row_ror:8 row_mask:0xf bank_mask:0xf bound_ctrl:1
	v_cndmask_b32_e64 v199, v199, v31, s[12:13]
	v_pk_fma_f32 v[34:35], v[178:179], v[30:31], v[34:35] op_sel_hi:[1,0,1]
	ds_read_b128 v[30:33], v28 offset:9216
	ds_read_b128 v[164:167], v28 offset:9472
	ds_read_b128 v[168:171], v28 offset:9728
	ds_read_b128 v[172:175], v28 offset:10240
	ds_read_b128 v[176:179], v28 offset:10496
	ds_read_b32 v198, v29 offset:9984
	s_waitcnt lgkmcnt(6)
	v_pk_mul_f32 v[190:191], v[190:191], v[34:35]
	v_pk_mul_f32 v[162:163], v[162:163], v[34:35]
	v_pk_fma_f32 v[188:189], v[188:189], v[196:197], v[190:191]
	v_pk_fma_f32 v[160:161], v[160:161], v[196:197], v[162:163]
	v_add_f32_e32 v206, v188, v189
	v_pk_mul_f32 v[162:163], v[180:181], v[196:197]
	v_add_f32_e32 v160, v160, v161
	v_add_f32_dpp v161, v206, v206 quad_perm:[1,0,3,2] row_mask:0xf bank_mask:0xf bound_ctrl:1
	v_pk_mul_f32 v[34:35], v[182:183], v[34:35]
	v_add_f32_dpp v160, v160, v160 quad_perm:[1,0,3,2] row_mask:0xf bank_mask:0xf bound_ctrl:1
	v_add_f32_dpp v161, v161, v161 quad_perm:[2,3,0,1] row_mask:0xf bank_mask:0xf bound_ctrl:1
	v_pk_fma_f32 v[34:35], v[186:187], v[200:201], v[34:35] op_sel_hi:[1,0,1]
	v_add_f32_dpp v160, v160, v160 quad_perm:[2,3,0,1] row_mask:0xf bank_mask:0xf bound_ctrl:1
	v_add_f32_dpp v161, v161, v161 row_ror:4 row_mask:0xf bank_mask:0xf bound_ctrl:1
	v_pk_fma_f32 v[162:163], v[184:185], v[200:201], v[162:163] op_sel_hi:[1,0,1]
	v_add_f32_dpp v180, v160, v160 row_ror:4 row_mask:0xf bank_mask:0xf bound_ctrl:1
	v_add_f32_dpp v160, v161, v161 row_ror:8 row_mask:0xf bank_mask:0xf bound_ctrl:1
	v_pk_fma_f32 v[196:197], v[192:193], v[160:161], v[162:163] op_sel_hi:[1,0,1]
	v_add_f32_dpp v161, v180, v180 row_ror:8 row_mask:0xf bank_mask:0xf bound_ctrl:1
	v_cndmask_b32_e64 v199, v199, v161, s[14:15]
	v_pk_fma_f32 v[34:35], v[194:195], v[160:161], v[34:35] op_sel_hi:[1,0,1]
	ds_read_b128 v[160:163], v28 offset:10752
	ds_read_b128 v[180:183], v28 offset:11008
	ds_read_b128 v[184:187], v28 offset:11264
	ds_read_b128 v[188:191], v28 offset:11776
	ds_read_b128 v[192:195], v28 offset:12032
	ds_read_b32 v200, v29 offset:11520
	s_waitcnt lgkmcnt(6)
; #define LAS __attribute__((address_space(3)))
; __device__ __forceinline__ void rwkv_scan_prompt(const Params& p, LAS unsigned char* lds, int bh, int rq) {
;     ...
;             for (int tk = 0; tk < TC; ++tk) {
;                 f32x4 nr4 = r4, nd4 = d4, nk4 = k4, na4 = a4, nb4 = b4; float nvv = vv;
;                 if (tk < TC - 1) {
;                     const LAS float* o = ob + (tk + 1) * 6 * 64;
;                     nr4 = *(const LAS f32x4*)(o + cg_ * 4); nd4 = *(const LAS f32x4*)(o + 64 + cg_ * 4); nk4 = *(const LAS f32x4*)(o + 128 + cg_ * 4);
;                     na4 = *(const LAS f32x4*)(o + 256 + cg_ * 4); nb4 = *(const LAS f32x4*)(o + 320 + cg_ * 4);
;                     nvv = o[192 + rq * 16 + rloc];
;                 }
;                 __builtin_amdgcn_sched_barrier(0);
;                 typedef float f32x2_ __attribute__((ext_vector_type(2)));
;                 f32x2_ ta = (f32x2_){S[0], S[1]} * (f32x2_){a4[0], a4[1]}; ta = (f32x2_){S[2], S[3]} * (f32x2_){a4[2], a4[3]} + ta;
;                 f32x2_ ty = (f32x2_){S[0], S[1]} * (f32x2_){rp[0], rp[1]}; ty = (f32x2_){S[2], S[3]} * (f32x2_){rp[2], rp[3]} + ty;
;                 const f32x4 T = S * d4 + vv * k4;
;                 float sa = ta[0] + ta[1];
;                 float yp = ty[0] + ty[1];
;                 sa = dpp_add<0xB1>(sa); yp = dpp_add<0xB1>(yp);
;                 sa = dpp_add<0x4E>(sa); yp = dpp_add<0x4E>(yp);
;                 sa = dpp_add<0x124>(sa); yp = dpp_add<0x124>(yp);
;                 sa = dpp_add<0x128>(sa); yp = dpp_add<0x128>(yp);
;                 if (tk > 0) yk[(tk - 1) >> 4] = (cg_ == ((tk - 1) & 15)) ? yp : yk[(tk - 1) >> 4];
;                 S = sa * b4 + T;
;                 rp = r4;
;                 r4 = nr4; d4 = nd4; k4 = nk4; a4 = na4; b4 = nb4; vv = nvv;
	v_pk_mul_f32 v[174:175], v[174:175], v[34:35]
	v_pk_mul_f32 v[26:27], v[26:27], v[34:35]
	v_pk_fma_f32 v[172:173], v[172:173], v[196:197], v[174:175]
	v_pk_fma_f32 v[24:25], v[24:25], v[196:197], v[26:27]
	v_add_f32_e32 v206, v172, v173
	v_pk_mul_f32 v[26:27], v[164:165], v[196:197]
	v_add_f32_e32 v24, v24, v25
	v_add_f32_dpp v25, v206, v206 quad_perm:[1,0,3,2] row_mask:0xf bank_mask:0xf bound_ctrl:1
	v_pk_mul_f32 v[34:35], v[166:167], v[34:35]
	v_add_f32_dpp v24, v24, v24 quad_perm:[1,0,3,2] row_mask:0xf bank_mask:0xf bound_ctrl:1
	v_add_f32_dpp v25, v25, v25 quad_perm:[2,3,0,1] row_mask:0xf bank_mask:0xf bound_ctrl:1
	v_pk_fma_f32 v[34:35], v[170:171], v[198:199], v[34:35] op_sel_hi:[1,0,1]
	v_add_f32_dpp v24, v24, v24 quad_perm:[2,3,0,1] row_mask:0xf bank_mask:0xf bound_ctrl:1
	v_add_f32_dpp v25, v25, v25 row_ror:4 row_mask:0xf bank_mask:0xf bound_ctrl:1
	v_pk_fma_f32 v[26:27], v[168:169], v[198:199], v[26:27] op_sel_hi:[1,0,1]
	v_add_f32_dpp v164, v24, v24 row_ror:4 row_mask:0xf bank_mask:0xf bound_ctrl:1
	v_add_f32_dpp v24, v25, v25 row_ror:8 row_mask:0xf bank_mask:0xf bound_ctrl:1
	v_pk_fma_f32 v[196:197], v[176:177], v[24:25], v[26:27] op_sel_hi:[1,0,1]
	v_add_f32_dpp v25, v164, v164 row_ror:8 row_mask:0xf bank_mask:0xf bound_ctrl:1
	v_cndmask_b32_e64 v199, v199, v25, s[16:17]
	v_pk_fma_f32 v[34:35], v[178:179], v[24:25], v[34:35] op_sel_hi:[1,0,1]
	ds_read_b128 v[24:27], v28 offset:12288
	ds_read_b128 v[164:167], v28 offset:12544
	ds_read_b128 v[168:171], v28 offset:12800
	ds_read_b128 v[172:175], v28 offset:13312
	ds_read_b128 v[176:179], v28 offset:13568
	ds_read_b32 v198, v29 offset:13056
	s_waitcnt lgkmcnt(6)
	v_pk_mul_f32 v[190:191], v[190:191], v[34:35]
	v_pk_mul_f32 v[32:33], v[32:33], v[34:35]
	v_pk_fma_f32 v[188:189], v[188:189], v[196:197], v[190:191]
	v_pk_fma_f32 v[30:31], v[30:31], v[196:197], v[32:33]
	v_add_f32_e32 v206, v188, v189
	v_pk_mul_f32 v[32:33], v[180:181], v[196:197]
	v_add_f32_e32 v30, v30, v31
	v_add_f32_dpp v31, v206, v206 quad_perm:[1,0,3,2] row_mask:0xf bank_mask:0xf bound_ctrl:1
	v_pk_mul_f32 v[34:35], v[182:183], v[34:35]
	v_add_f32_dpp v30, v30, v30 quad_perm:[1,0,3,2] row_mask:0xf bank_mask:0xf bound_ctrl:1
	v_add_f32_dpp v31, v31, v31 quad_perm:[2,3,0,1] row_mask:0xf bank_mask:0xf bound_ctrl:1
	v_pk_fma_f32 v[34:35], v[186:187], v[200:201], v[34:35] op_sel_hi:[1,0,1]
	v_add_f32_dpp v30, v30, v30 quad_perm:[2,3,0,1] row_mask:0xf bank_mask:0xf bound_ctrl:1
	v_add_f32_dpp v31, v31, v31 row_ror:4 row_mask:0xf bank_mask:0xf bound_ctrl:1
	v_pk_fma_f32 v[32:33], v[184:185], v[200:201], v[32:33] op_sel_hi:[1,0,1]
	v_add_f32_dpp v180, v30, v30 row_ror:4 row_mask:0xf bank_mask:0xf bound_ctrl:1
	v_add_f32_dpp v30, v31, v31 row_ror:8 row_mask:0xf bank_mask:0xf bound_ctrl:1
	v_pk_fma_f32 v[196:197], v[192:193], v[30:31], v[32:33] op_sel_hi:[1,0,1]
	v_add_f32_dpp v31, v180, v180 row_ror:8 row_mask:0xf bank_mask:0xf bound_ctrl:1
	v_cndmask_b32_e64 v199, v199, v31, s[18:19]
	v_pk_fma_f32 v[34:35], v[194:195], v[30:31], v[34:35] op_sel_hi:[1,0,1]
	ds_read_b128 v[30:33], v28 offset:13824
	ds_read_b128 v[180:183], v28 offset:14080
	ds_read_b128 v[184:187], v28 offset:14336
	ds_read_b128 v[188:191], v28 offset:14848
	ds_read_b128 v[192:195], v28 offset:15104
	ds_read_b32 v200, v29 offset:14592
	s_waitcnt lgkmcnt(6)
	v_pk_mul_f32 v[174:175], v[174:175], v[34:35]
	v_pk_mul_f32 v[162:163], v[162:163], v[34:35]
	v_pk_fma_f32 v[172:173], v[172:173], v[196:197], v[174:175]
	v_pk_fma_f32 v[160:161], v[160:161], v[196:197], v[162:163]
	v_add_f32_e32 v206, v172, v173
	v_pk_mul_f32 v[162:163], v[164:165], v[196:197]
	v_add_f32_e32 v160, v160, v161
	v_add_f32_dpp v161, v206, v206 quad_perm:[1,0,3,2] row_mask:0xf bank_mask:0xf bound_ctrl:1
	v_pk_mul_f32 v[34:35], v[166:167], v[34:35]
	v_add_f32_dpp v160, v160, v160 quad_perm:[1,0,3,2] row_mask:0xf bank_mask:0xf bound_ctrl:1
	v_add_f32_dpp v161, v161, v161 quad_perm:[2,3,0,1] row_mask:0xf bank_mask:0xf bound_ctrl:1
	v_pk_fma_f32 v[34:35], v[170:171], v[198:199], v[34:35] op_sel_hi:[1,0,1]
	v_add_f32_dpp v160, v160, v160 quad_perm:[2,3,0,1] row_mask:0xf bank_mask:0xf bound_ctrl:1
	v_add_f32_dpp v161, v161, v161 row_ror:4 row_mask:0xf bank_mask:0xf bound_ctrl:1
	v_pk_fma_f32 v[162:163], v[168:169], v[198:199], v[162:163] op_sel_hi:[1,0,1]
	v_add_f32_dpp v164, v160, v160 row_ror:4 row_mask:0xf bank_mask:0xf bound_ctrl:1
	v_add_f32_dpp v160, v161, v161 row_ror:8 row_mask:0xf bank_mask:0xf bound_ctrl:1
	v_pk_fma_f32 v[196:197], v[176:177], v[160:161], v[162:163] op_sel_hi:[1,0,1]
	v_add_f32_dpp v161, v164, v164 row_ror:8 row_mask:0xf bank_mask:0xf bound_ctrl:1
	v_cndmask_b32_e64 v199, v199, v161, s[20:21]
	v_pk_fma_f32 v[34:35], v[178:179], v[160:161], v[34:35] op_sel_hi:[1,0,1]
	ds_read_b128 v[160:163], v28 offset:15360
	ds_read_b128 v[164:167], v28 offset:15616
	ds_read_b128 v[168:171], v28 offset:15872
	ds_read_b128 v[172:175], v28 offset:16384
	ds_read_b128 v[176:179], v28 offset:16640
	ds_read_b32 v198, v29 offset:16128
	s_waitcnt lgkmcnt(6)
; #define LAS __attribute__((address_space(3)))
; __device__ __forceinline__ void rwkv_scan_prompt(const Params& p, LAS unsigned char* lds, int bh, int rq) {
;     ...
;             for (int tk = 0; tk < TC; ++tk) {
;                 f32x4 nr4 = r4, nd4 = d4, nk4 = k4, na4 = a4, nb4 = b4; float nvv = vv;
;                 if (tk < TC - 1) {
;                     const LAS float* o = ob + (tk + 1) * 6 * 64;
;                     nr4 = *(const LAS f32x4*)(o + cg_ * 4); nd4 = *(const LAS f32x4*)(o + 64 + cg_ * 4); nk4 = *(const LAS f32x4*)(o + 128 + cg_ * 4);
;                     na4 = *(const LAS f32x4*)(o + 256 + cg_ * 4); nb4 = *(const LAS f32x4*)(o + 320 + cg_ * 4);
;                     nvv = o[192 + rq * 16 + rloc];
;                 }
;                 __builtin_amdgcn_sched_barrier(0);
;                 typedef float f32x2_ __attribute__((ext_vector_type(2)));
;                 f32x2_ ta = (f32x2_){S[0], S[1]} * (f32x2_){a4[0], a4[1]}; ta = (f32x2_){S[2], S[3]} * (f32x2_){a4[2], a4[3]} + ta;
;                 f32x2_ ty = (f32x2_){S[0], S[1]} * (f32x2_){rp[0], rp[1]}; ty = (f32x2_){S[2], S[3]} * (f32x2_){rp[2], rp[3]} + ty;
;                 const f32x4 T = S * d4 + vv * k4;
;                 float sa = ta[0] + ta[1];
;                 float yp = ty[0] + ty[1];
;                 sa = dpp_add<0xB1>(sa); yp = dpp_add<0xB1>(yp);
;                 sa = dpp_add<0x4E>(sa); yp = dpp_add<0x4E>(yp);
;                 sa = dpp_add<0x124>(sa); yp = dpp_add<0x124>(yp);
;                 sa = dpp_add<0x128>(sa); yp = dpp_add<0x128>(yp);
;                 if (tk > 0) yk[(tk - 1) >> 4] = (cg_ == ((tk - 1) & 15)) ? yp : yk[(tk - 1) >> 4];
;                 S = sa * b4 + T;
;                 rp = r4;
;                 r4 = nr4; d4 = nd4; k4 = nk4; a4 = na4; b4 = nb4; vv = nvv;
	v_pk_mul_f32 v[190:191], v[190:191], v[34:35]
	v_pk_mul_f32 v[26:27], v[26:27], v[34:35]
	v_pk_fma_f32 v[188:189], v[188:189], v[196:197], v[190:191]
	v_pk_fma_f32 v[24:25], v[24:25], v[196:197], v[26:27]
	v_add_f32_e32 v206, v188, v189
	v_pk_mul_f32 v[26:27], v[180:181], v[196:197]
	v_add_f32_e32 v24, v24, v25
	v_add_f32_dpp v25, v206, v206 quad_perm:[1,0,3,2] row_mask:0xf bank_mask:0xf bound_ctrl:1
	v_pk_mul_f32 v[34:35], v[182:183], v[34:35]
	v_add_f32_dpp v24, v24, v24 quad_perm:[1,0,3,2] row_mask:0xf bank_mask:0xf bound_ctrl:1
	v_add_f32_dpp v25, v25, v25 quad_perm:[2,3,0,1] row_mask:0xf bank_mask:0xf bound_ctrl:1
	v_pk_fma_f32 v[34:35], v[186:187], v[200:201], v[34:35] op_sel_hi:[1,0,1]
	v_add_f32_dpp v24, v24, v24 quad_perm:[2,3,0,1] row_mask:0xf bank_mask:0xf bound_ctrl:1
	v_add_f32_dpp v25, v25, v25 row_ror:4 row_mask:0xf bank_mask:0xf bound_ctrl:1
	v_pk_fma_f32 v[26:27], v[184:185], v[200:201], v[26:27] op_sel_hi:[1,0,1]
	v_add_f32_dpp v180, v24, v24 row_ror:4 row_mask:0xf bank_mask:0xf bound_ctrl:1
	v_add_f32_dpp v24, v25, v25 row_ror:8 row_mask:0xf bank_mask:0xf bound_ctrl:1
	v_pk_fma_f32 v[196:197], v[192:193], v[24:25], v[26:27] op_sel_hi:[1,0,1]
	v_add_f32_dpp v25, v180, v180 row_ror:8 row_mask:0xf bank_mask:0xf bound_ctrl:1
	v_cndmask_b32_e64 v199, v199, v25, s[22:23]
	v_pk_fma_f32 v[34:35], v[194:195], v[24:25], v[34:35] op_sel_hi:[1,0,1]
	ds_read_b128 v[24:27], v28 offset:16896
	ds_read_b128 v[180:183], v28 offset:17152
	ds_read_b128 v[184:187], v28 offset:17408
	ds_read_b128 v[188:191], v28 offset:17920
	ds_read_b128 v[192:195], v28 offset:18176
	ds_read_b32 v200, v29 offset:17664
	s_waitcnt lgkmcnt(6)
	v_pk_mul_f32 v[174:175], v[174:175], v[34:35]
	v_pk_mul_f32 v[32:33], v[32:33], v[34:35]
	v_pk_fma_f32 v[172:173], v[172:173], v[196:197], v[174:175]
	v_pk_fma_f32 v[30:31], v[30:31], v[196:197], v[32:33]
	v_add_f32_e32 v206, v172, v173
	v_pk_mul_f32 v[32:33], v[164:165], v[196:197]
	v_add_f32_e32 v30, v30, v31
	v_add_f32_dpp v31, v206, v206 quad_perm:[1,0,3,2] row_mask:0xf bank_mask:0xf bound_ctrl:1
	v_pk_mul_f32 v[34:35], v[166:167], v[34:35]
	v_add_f32_dpp v30, v30, v30 quad_perm:[1,0,3,2] row_mask:0xf bank_mask:0xf bound_ctrl:1
	v_add_f32_dpp v31, v31, v31 quad_perm:[2,3,0,1] row_mask:0xf bank_mask:0xf bound_ctrl:1
	v_pk_fma_f32 v[34:35], v[170:171], v[198:199], v[34:35] op_sel_hi:[1,0,1]
	v_add_f32_dpp v30, v30, v30 quad_perm:[2,3,0,1] row_mask:0xf bank_mask:0xf bound_ctrl:1
	v_add_f32_dpp v31, v31, v31 row_ror:4 row_mask:0xf bank_mask:0xf bound_ctrl:1
	v_pk_fma_f32 v[32:33], v[168:169], v[198:199], v[32:33] op_sel_hi:[1,0,1]
	v_add_f32_dpp v164, v30, v30 row_ror:4 row_mask:0xf bank_mask:0xf bound_ctrl:1
	v_add_f32_dpp v30, v31, v31 row_ror:8 row_mask:0xf bank_mask:0xf bound_ctrl:1
	v_pk_fma_f32 v[196:197], v[176:177], v[30:31], v[32:33] op_sel_hi:[1,0,1]
	v_add_f32_dpp v31, v164, v164 row_ror:8 row_mask:0xf bank_mask:0xf bound_ctrl:1
	v_cndmask_b32_e64 v199, v199, v31, s[24:25]
	v_pk_fma_f32 v[34:35], v[178:179], v[30:31], v[34:35] op_sel_hi:[1,0,1]
	ds_read_b128 v[30:33], v28 offset:18432
	ds_read_b128 v[164:167], v28 offset:18688
	ds_read_b128 v[168:171], v28 offset:18944
	ds_read_b128 v[172:175], v28 offset:19456
	ds_read_b128 v[176:179], v28 offset:19712
	ds_read_b32 v198, v29 offset:19200
	s_waitcnt lgkmcnt(6)
	v_pk_mul_f32 v[190:191], v[190:191], v[34:35]
	v_pk_mul_f32 v[162:163], v[162:163], v[34:35]
	v_pk_fma_f32 v[188:189], v[188:189], v[196:197], v[190:191]
	v_pk_fma_f32 v[160:161], v[160:161], v[196:197], v[162:163]
	v_add_f32_e32 v206, v188, v189
	v_pk_mul_f32 v[162:163], v[180:181], v[196:197]
	v_add_f32_e32 v160, v160, v161
	v_add_f32_dpp v161, v206, v206 quad_perm:[1,0,3,2] row_mask:0xf bank_mask:0xf bound_ctrl:1
	v_pk_mul_f32 v[34:35], v[182:183], v[34:35]
	v_add_f32_dpp v160, v160, v160 quad_perm:[1,0,3,2] row_mask:0xf bank_mask:0xf bound_ctrl:1
	v_add_f32_dpp v161, v161, v161 quad_perm:[2,3,0,1] row_mask:0xf bank_mask:0xf bound_ctrl:1
	v_pk_fma_f32 v[34:35], v[186:187], v[200:201], v[34:35] op_sel_hi:[1,0,1]
	v_add_f32_dpp v160, v160, v160 quad_perm:[2,3,0,1] row_mask:0xf bank_mask:0xf bound_ctrl:1
	v_add_f32_dpp v161, v161, v161 row_ror:4 row_mask:0xf bank_mask:0xf bound_ctrl:1
	v_pk_fma_f32 v[162:163], v[184:185], v[200:201], v[162:163] op_sel_hi:[1,0,1]
	v_add_f32_dpp v180, v160, v160 row_ror:4 row_mask:0xf bank_mask:0xf bound_ctrl:1
	v_add_f32_dpp v160, v161, v161 row_ror:8 row_mask:0xf bank_mask:0xf bound_ctrl:1
	v_pk_fma_f32 v[196:197], v[192:193], v[160:161], v[162:163] op_sel_hi:[1,0,1]
	v_add_f32_dpp v161, v180, v180 row_ror:8 row_mask:0xf bank_mask:0xf bound_ctrl:1
	v_cndmask_b32_e64 v199, v199, v161, s[26:27]
	v_pk_fma_f32 v[34:35], v[194:195], v[160:161], v[34:35] op_sel_hi:[1,0,1]
	ds_read_b128 v[160:163], v28 offset:19968
	ds_read_b128 v[180:183], v28 offset:20224
	ds_read_b128 v[184:187], v28 offset:20480
	ds_read_b128 v[188:191], v28 offset:20992
	ds_read_b128 v[192:195], v28 offset:21248
	ds_read_b32 v200, v29 offset:20736
	s_waitcnt lgkmcnt(6)
; #define LAS __attribute__((address_space(3)))
; __device__ __forceinline__ void rwkv_scan_prompt(const Params& p, LAS unsigned char* lds, int bh, int rq) {
;     ...
;             for (int tk = 0; tk < TC; ++tk) {
;                 f32x4 nr4 = r4, nd4 = d4, nk4 = k4, na4 = a4, nb4 = b4; float nvv = vv;
;                 if (tk < TC - 1) {
;                     const LAS float* o = ob + (tk + 1) * 6 * 64;
;                     nr4 = *(const LAS f32x4*)(o + cg_ * 4); nd4 = *(const LAS f32x4*)(o + 64 + cg_ * 4); nk4 = *(const LAS f32x4*)(o + 128 + cg_ * 4);
;                     na4 = *(const LAS f32x4*)(o + 256 + cg_ * 4); nb4 = *(const LAS f32x4*)(o + 320 + cg_ * 4);
;                     nvv = o[192 + rq * 16 + rloc];
;                 }
;                 __builtin_amdgcn_sched_barrier(0);
;                 typedef float f32x2_ __attribute__((ext_vector_type(2)));
;                 f32x2_ ta = (f32x2_){S[0], S[1]} * (f32x2_){a4[0], a4[1]}; ta = (f32x2_){S[2], S[3]} * (f32x2_){a4[2], a4[3]} + ta;
;                 f32x2_ ty = (f32x2_){S[0], S[1]} * (f32x2_){rp[0], rp[1]}; ty = (f32x2_){S[2], S[3]} * (f32x2_){rp[2], rp[3]} + ty;
;                 const f32x4 T = S * d4 + vv * k4;
;                 float sa = ta[0] + ta[1];
;                 float yp = ty[0] + ty[1];
;                 sa = dpp_add<0xB1>(sa); yp = dpp_add<0xB1>(yp);
;                 sa = dpp_add<0x4E>(sa); yp = dpp_add<0x4E>(yp);
;                 sa = dpp_add<0x124>(sa); yp = dpp_add<0x124>(yp);
;                 sa = dpp_add<0x128>(sa); yp = dpp_add<0x128>(yp);
;                 if (tk > 0) yk[(tk - 1) >> 4] = (cg_ == ((tk - 1) & 15)) ? yp : yk[(tk - 1) >> 4];
;                 S = sa * b4 + T;
;                 rp = r4;
;                 r4 = nr4; d4 = nd4; k4 = nk4; a4 = na4; b4 = nb4; vv = nvv;
	v_pk_mul_f32 v[174:175], v[174:175], v[34:35]
	v_pk_mul_f32 v[26:27], v[26:27], v[34:35]
	v_pk_fma_f32 v[172:173], v[172:173], v[196:197], v[174:175]
	v_pk_fma_f32 v[24:25], v[24:25], v[196:197], v[26:27]
	v_add_f32_e32 v206, v172, v173
	v_pk_mul_f32 v[26:27], v[164:165], v[196:197]
	v_add_f32_e32 v24, v24, v25
	v_add_f32_dpp v25, v206, v206 quad_perm:[1,0,3,2] row_mask:0xf bank_mask:0xf bound_ctrl:1
	v_pk_mul_f32 v[34:35], v[166:167], v[34:35]
	v_add_f32_dpp v24, v24, v24 quad_perm:[1,0,3,2] row_mask:0xf bank_mask:0xf bound_ctrl:1
	v_add_f32_dpp v25, v25, v25 quad_perm:[2,3,0,1] row_mask:0xf bank_mask:0xf bound_ctrl:1
	v_pk_fma_f32 v[34:35], v[170:171], v[198:199], v[34:35] op_sel_hi:[1,0,1]
	v_add_f32_dpp v24, v24, v24 quad_perm:[2,3,0,1] row_mask:0xf bank_mask:0xf bound_ctrl:1
	v_add_f32_dpp v25, v25, v25 row_ror:4 row_mask:0xf bank_mask:0xf bound_ctrl:1
	v_pk_fma_f32 v[26:27], v[168:169], v[198:199], v[26:27] op_sel_hi:[1,0,1]
	v_add_f32_dpp v164, v24, v24 row_ror:4 row_mask:0xf bank_mask:0xf bound_ctrl:1
	v_add_f32_dpp v24, v25, v25 row_ror:8 row_mask:0xf bank_mask:0xf bound_ctrl:1
	v_pk_fma_f32 v[196:197], v[176:177], v[24:25], v[26:27] op_sel_hi:[1,0,1]
	v_add_f32_dpp v25, v164, v164 row_ror:8 row_mask:0xf bank_mask:0xf bound_ctrl:1
	v_cndmask_b32_e64 v199, v199, v25, s[28:29]
	v_pk_fma_f32 v[34:35], v[178:179], v[24:25], v[34:35] op_sel_hi:[1,0,1]
	ds_read_b128 v[24:27], v28 offset:21504
	ds_read_b128 v[164:167], v28 offset:21760
	ds_read_b128 v[168:171], v28 offset:22016
	ds_read_b128 v[172:175], v28 offset:22528
	ds_read_b128 v[176:179], v28 offset:22784
	ds_read_b32 v198, v29 offset:22272
	s_waitcnt lgkmcnt(6)
	v_pk_mul_f32 v[190:191], v[190:191], v[34:35]
	v_pk_mul_f32 v[32:33], v[32:33], v[34:35]
	v_pk_fma_f32 v[188:189], v[188:189], v[196:197], v[190:191]
	v_pk_fma_f32 v[30:31], v[30:31], v[196:197], v[32:33]
	v_add_f32_e32 v206, v188, v189
	v_pk_mul_f32 v[32:33], v[180:181], v[196:197]
	v_add_f32_e32 v30, v30, v31
	v_add_f32_dpp v31, v206, v206 quad_perm:[1,0,3,2] row_mask:0xf bank_mask:0xf bound_ctrl:1
	v_pk_mul_f32 v[34:35], v[182:183], v[34:35]
	v_add_f32_dpp v30, v30, v30 quad_perm:[1,0,3,2] row_mask:0xf bank_mask:0xf bound_ctrl:1
	v_add_f32_dpp v31, v31, v31 quad_perm:[2,3,0,1] row_mask:0xf bank_mask:0xf bound_ctrl:1
	v_pk_fma_f32 v[34:35], v[186:187], v[200:201], v[34:35] op_sel_hi:[1,0,1]
	v_add_f32_dpp v30, v30, v30 quad_perm:[2,3,0,1] row_mask:0xf bank_mask:0xf bound_ctrl:1
	v_add_f32_dpp v31, v31, v31 row_ror:4 row_mask:0xf bank_mask:0xf bound_ctrl:1
	v_pk_fma_f32 v[32:33], v[184:185], v[200:201], v[32:33] op_sel_hi:[1,0,1]
	v_add_f32_dpp v180, v30, v30 row_ror:4 row_mask:0xf bank_mask:0xf bound_ctrl:1
	v_add_f32_dpp v30, v31, v31 row_ror:8 row_mask:0xf bank_mask:0xf bound_ctrl:1
	v_pk_fma_f32 v[196:197], v[192:193], v[30:31], v[32:33] op_sel_hi:[1,0,1]
	v_add_f32_dpp v31, v180, v180 row_ror:8 row_mask:0xf bank_mask:0xf bound_ctrl:1
	v_cndmask_b32_e64 v199, v199, v31, s[30:31]
	v_pk_fma_f32 v[34:35], v[194:195], v[30:31], v[34:35] op_sel_hi:[1,0,1]
	ds_read_b128 v[30:33], v28 offset:23040
	ds_read_b128 v[180:183], v28 offset:23296
	ds_read_b128 v[184:187], v28 offset:23552
	ds_read_b128 v[188:191], v28 offset:24064
	ds_read_b128 v[192:195], v28 offset:24320
	ds_read_b32 v200, v29 offset:23808
	s_waitcnt lgkmcnt(6)
	v_pk_mul_f32 v[174:175], v[174:175], v[34:35]
	v_pk_mul_f32 v[162:163], v[162:163], v[34:35]
	v_pk_fma_f32 v[172:173], v[172:173], v[196:197], v[174:175]
	v_pk_fma_f32 v[160:161], v[160:161], v[196:197], v[162:163]
	v_add_f32_e32 v206, v172, v173
	v_pk_mul_f32 v[162:163], v[164:165], v[196:197]
	v_add_f32_e32 v160, v160, v161
	v_add_f32_dpp v161, v206, v206 quad_perm:[1,0,3,2] row_mask:0xf bank_mask:0xf bound_ctrl:1
	v_pk_mul_f32 v[34:35], v[166:167], v[34:35]
	v_add_f32_dpp v160, v160, v160 quad_perm:[1,0,3,2] row_mask:0xf bank_mask:0xf bound_ctrl:1
	v_add_f32_dpp v161, v161, v161 quad_perm:[2,3,0,1] row_mask:0xf bank_mask:0xf bound_ctrl:1
	v_pk_fma_f32 v[34:35], v[170:171], v[198:199], v[34:35] op_sel_hi:[1,0,1]
	v_add_f32_dpp v160, v160, v160 quad_perm:[2,3,0,1] row_mask:0xf bank_mask:0xf bound_ctrl:1
	v_add_f32_dpp v161, v161, v161 row_ror:4 row_mask:0xf bank_mask:0xf bound_ctrl:1
	v_pk_fma_f32 v[162:163], v[168:169], v[198:199], v[162:163] op_sel_hi:[1,0,1]
	v_add_f32_dpp v164, v160, v160 row_ror:4 row_mask:0xf bank_mask:0xf bound_ctrl:1
	v_add_f32_dpp v160, v161, v161 row_ror:8 row_mask:0xf bank_mask:0xf bound_ctrl:1
	v_pk_fma_f32 v[196:197], v[176:177], v[160:161], v[162:163] op_sel_hi:[1,0,1]
	v_add_f32_dpp v161, v164, v164 row_ror:8 row_mask:0xf bank_mask:0xf bound_ctrl:1
	v_cndmask_b32_e64 v199, v199, v161, s[34:35]
	v_pk_fma_f32 v[34:35], v[178:179], v[160:161], v[34:35] op_sel_hi:[1,0,1]
	ds_read_b128 v[160:163], v28 offset:24576
	ds_read_b128 v[164:167], v28 offset:24832
	ds_read_b128 v[168:171], v28 offset:25088
	ds_read_b128 v[172:175], v28 offset:25600
	ds_read_b128 v[176:179], v28 offset:25856
	ds_read_b32 v198, v29 offset:25344
	s_waitcnt lgkmcnt(6)
; #define LAS __attribute__((address_space(3)))
; __device__ __forceinline__ void rwkv_scan_prompt(const Params& p, LAS unsigned char* lds, int bh, int rq) {
;     ...
;             for (int tk = 0; tk < TC; ++tk) {
;                 f32x4 nr4 = r4, nd4 = d4, nk4 = k4, na4 = a4, nb4 = b4; float nvv = vv;
;                 if (tk < TC - 1) {
;                     const LAS float* o = ob + (tk + 1) * 6 * 64;
;                     nr4 = *(const LAS f32x4*)(o + cg_ * 4); nd4 = *(const LAS f32x4*)(o + 64 + cg_ * 4); nk4 = *(const LAS f32x4*)(o + 128 + cg_ * 4);
;                     na4 = *(const LAS f32x4*)(o + 256 + cg_ * 4); nb4 = *(const LAS f32x4*)(o + 320 + cg_ * 4);
;                     nvv = o[192 + rq * 16 + rloc];
;                 }
;                 __builtin_amdgcn_sched_barrier(0);
;                 typedef float f32x2_ __attribute__((ext_vector_type(2)));
;                 f32x2_ ta = (f32x2_){S[0], S[1]} * (f32x2_){a4[0], a4[1]}; ta = (f32x2_){S[2], S[3]} * (f32x2_){a4[2], a4[3]} + ta;
;                 f32x2_ ty = (f32x2_){S[0], S[1]} * (f32x2_){rp[0], rp[1]}; ty = (f32x2_){S[2], S[3]} * (f32x2_){rp[2], rp[3]} + ty;
;                 const f32x4 T = S * d4 + vv * k4;
;                 float sa = ta[0] + ta[1];
;                 float yp = ty[0] + ty[1];
;                 sa = dpp_add<0xB1>(sa); yp = dpp_add<0xB1>(yp);
;                 sa = dpp_add<0x4E>(sa); yp = dpp_add<0x4E>(yp);
;                 sa = dpp_add<0x124>(sa); yp = dpp_add<0x124>(yp);
;                 sa = dpp_add<0x128>(sa); yp = dpp_add<0x128>(yp);
;                 if (tk > 0) yk[(tk - 1) >> 4] = (cg_ == ((tk - 1) & 15)) ? yp : yk[(tk - 1) >> 4];
;                 S = sa * b4 + T;
;                 rp = r4;
;                 r4 = nr4; d4 = nd4; k4 = nk4; a4 = na4; b4 = nb4; vv = nvv;
	v_pk_mul_f32 v[190:191], v[190:191], v[34:35]
	v_pk_mul_f32 v[26:27], v[26:27], v[34:35]
	v_pk_fma_f32 v[188:189], v[188:189], v[196:197], v[190:191]
	v_pk_fma_f32 v[24:25], v[24:25], v[196:197], v[26:27]
	v_add_f32_e32 v206, v188, v189
	v_pk_mul_f32 v[26:27], v[180:181], v[196:197]
	v_add_f32_e32 v24, v24, v25
	v_add_f32_dpp v25, v206, v206 quad_perm:[1,0,3,2] row_mask:0xf bank_mask:0xf bound_ctrl:1
	v_pk_mul_f32 v[34:35], v[182:183], v[34:35]
	v_add_f32_dpp v24, v24, v24 quad_perm:[1,0,3,2] row_mask:0xf bank_mask:0xf bound_ctrl:1
	v_add_f32_dpp v25, v25, v25 quad_perm:[2,3,0,1] row_mask:0xf bank_mask:0xf bound_ctrl:1
	v_pk_fma_f32 v[34:35], v[186:187], v[200:201], v[34:35] op_sel_hi:[1,0,1]
	v_add_f32_dpp v24, v24, v24 quad_perm:[2,3,0,1] row_mask:0xf bank_mask:0xf bound_ctrl:1
	v_add_f32_dpp v25, v25, v25 row_ror:4 row_mask:0xf bank_mask:0xf bound_ctrl:1
	v_pk_fma_f32 v[26:27], v[184:185], v[200:201], v[26:27] op_sel_hi:[1,0,1]
	v_add_f32_dpp v180, v24, v24 row_ror:4 row_mask:0xf bank_mask:0xf bound_ctrl:1
	v_add_f32_dpp v24, v25, v25 row_ror:8 row_mask:0xf bank_mask:0xf bound_ctrl:1
	v_pk_fma_f32 v[196:197], v[192:193], v[24:25], v[26:27] op_sel_hi:[1,0,1]
	v_add_f32_dpp v25, v180, v180 row_ror:8 row_mask:0xf bank_mask:0xf bound_ctrl:1
	v_cndmask_b32_e64 v199, v199, v25, s[36:37]
	v_pk_fma_f32 v[34:35], v[194:195], v[24:25], v[34:35] op_sel_hi:[1,0,1]
	ds_read_b128 v[24:27], v28 offset:26112
	ds_read_b128 v[180:183], v28 offset:26368
	ds_read_b128 v[184:187], v28 offset:26624
	ds_read_b128 v[188:191], v28 offset:27136
	ds_read_b128 v[192:195], v28 offset:27392
	ds_read_b32 v200, v29 offset:26880
	s_waitcnt lgkmcnt(6)
	v_pk_mul_f32 v[174:175], v[174:175], v[34:35]
	v_pk_mul_f32 v[32:33], v[32:33], v[34:35]
	v_pk_fma_f32 v[172:173], v[172:173], v[196:197], v[174:175]
	v_pk_fma_f32 v[30:31], v[30:31], v[196:197], v[32:33]
	v_add_f32_e32 v206, v172, v173
	v_pk_mul_f32 v[32:33], v[164:165], v[196:197]
	v_add_f32_e32 v30, v30, v31
	v_add_f32_dpp v31, v206, v206 quad_perm:[1,0,3,2] row_mask:0xf bank_mask:0xf bound_ctrl:1
	v_pk_mul_f32 v[34:35], v[166:167], v[34:35]
	v_add_f32_dpp v30, v30, v30 quad_perm:[1,0,3,2] row_mask:0xf bank_mask:0xf bound_ctrl:1
	v_add_f32_dpp v31, v31, v31 quad_perm:[2,3,0,1] row_mask:0xf bank_mask:0xf bound_ctrl:1
	v_pk_fma_f32 v[34:35], v[170:171], v[198:199], v[34:35] op_sel_hi:[1,0,1]
	v_add_f32_dpp v30, v30, v30 quad_perm:[2,3,0,1] row_mask:0xf bank_mask:0xf bound_ctrl:1
	v_add_f32_dpp v31, v31, v31 row_ror:4 row_mask:0xf bank_mask:0xf bound_ctrl:1
	v_pk_fma_f32 v[32:33], v[168:169], v[198:199], v[32:33] op_sel_hi:[1,0,1]
	v_add_f32_dpp v30, v30, v30 row_ror:4 row_mask:0xf bank_mask:0xf bound_ctrl:1
	v_add_f32_dpp v164, v31, v31 row_ror:8 row_mask:0xf bank_mask:0xf bound_ctrl:1
	v_pk_fma_f32 v[196:197], v[176:177], v[164:165], v[32:33] op_sel_hi:[1,0,1]
	v_add_f32_dpp v30, v30, v30 row_ror:8 row_mask:0xf bank_mask:0xf bound_ctrl:1
	v_cndmask_b32_e64 v30, v199, v30, s[4:5]
	v_pk_fma_f32 v[198:199], v[178:179], v[164:165], v[34:35] op_sel_hi:[1,0,1]
	ds_read_b128 v[32:35], v28 offset:27648
	ds_read_b128 v[164:167], v28 offset:27904
	ds_read_b128 v[168:171], v28 offset:28160
	ds_read_b128 v[172:175], v28 offset:28672
	ds_read_b128 v[176:179], v28 offset:28928
	ds_read_b32 v202, v29 offset:28416
	s_waitcnt lgkmcnt(6)
	v_pk_mul_f32 v[190:191], v[190:191], v[198:199]
	v_pk_mul_f32 v[162:163], v[162:163], v[198:199]
	v_pk_fma_f32 v[188:189], v[188:189], v[196:197], v[190:191]
	v_pk_fma_f32 v[160:161], v[160:161], v[196:197], v[162:163]
	v_add_f32_e32 v31, v188, v189
	v_add_f32_e32 v160, v160, v161
	v_pk_mul_f32 v[162:163], v[180:181], v[196:197]
	v_add_f32_dpp v31, v31, v31 quad_perm:[1,0,3,2] row_mask:0xf bank_mask:0xf bound_ctrl:1
	v_add_f32_dpp v160, v160, v160 quad_perm:[1,0,3,2] row_mask:0xf bank_mask:0xf bound_ctrl:1
	v_pk_mul_f32 v[180:181], v[182:183], v[198:199]
	v_add_f32_dpp v31, v31, v31 quad_perm:[2,3,0,1] row_mask:0xf bank_mask:0xf bound_ctrl:1
	v_add_f32_dpp v160, v160, v160 quad_perm:[2,3,0,1] row_mask:0xf bank_mask:0xf bound_ctrl:1
	v_pk_fma_f32 v[180:181], v[186:187], v[200:201], v[180:181] op_sel_hi:[1,0,1]
	v_add_f32_dpp v31, v31, v31 row_ror:4 row_mask:0xf bank_mask:0xf bound_ctrl:1
	v_pk_fma_f32 v[162:163], v[184:185], v[200:201], v[162:163] op_sel_hi:[1,0,1]
	v_add_f32_dpp v161, v160, v160 row_ror:4 row_mask:0xf bank_mask:0xf bound_ctrl:1
	v_add_f32_dpp v160, v31, v31 row_ror:8 row_mask:0xf bank_mask:0xf bound_ctrl:1
	v_pk_fma_f32 v[196:197], v[192:193], v[160:161], v[162:163] op_sel_hi:[1,0,1]
	v_add_f32_dpp v31, v161, v161 row_ror:8 row_mask:0xf bank_mask:0xf bound_ctrl:1
	v_pk_fma_f32 v[198:199], v[194:195], v[160:161], v[180:181] op_sel_hi:[1,0,1]
	ds_read_b128 v[160:163], v28 offset:29184
	ds_read_b128 v[180:183], v28 offset:29440
	ds_read_b128 v[184:187], v28 offset:29696
	ds_read_b128 v[188:191], v28 offset:30208
	ds_read_b128 v[192:195], v28 offset:30464
	ds_read_b32 v200, v29 offset:29952
	v_cndmask_b32_e64 v31, 0, v31, s[6:7]
	s_waitcnt lgkmcnt(6)
; #define LAS __attribute__((address_space(3)))
; __device__ __forceinline__ void rwkv_scan_prompt(const Params& p, LAS unsigned char* lds, int bh, int rq) {
;     ...
;             for (int tk = 0; tk < TC; ++tk) {
;                 f32x4 nr4 = r4, nd4 = d4, nk4 = k4, na4 = a4, nb4 = b4; float nvv = vv;
;                 if (tk < TC - 1) {
;                     const LAS float* o = ob + (tk + 1) * 6 * 64;
;                     nr4 = *(const LAS f32x4*)(o + cg_ * 4); nd4 = *(const LAS f32x4*)(o + 64 + cg_ * 4); nk4 = *(const LAS f32x4*)(o + 128 + cg_ * 4);
;                     na4 = *(const LAS f32x4*)(o + 256 + cg_ * 4); nb4 = *(const LAS f32x4*)(o + 320 + cg_ * 4);
;                     nvv = o[192 + rq * 16 + rloc];
;                 }
;                 __builtin_amdgcn_sched_barrier(0);
;                 typedef float f32x2_ __attribute__((ext_vector_type(2)));
;                 f32x2_ ta = (f32x2_){S[0], S[1]} * (f32x2_){a4[0], a4[1]}; ta = (f32x2_){S[2], S[3]} * (f32x2_){a4[2], a4[3]} + ta;
;                 f32x2_ ty = (f32x2_){S[0], S[1]} * (f32x2_){rp[0], rp[1]}; ty = (f32x2_){S[2], S[3]} * (f32x2_){rp[2], rp[3]} + ty;
;                 const f32x4 T = S * d4 + vv * k4;
;                 float sa = ta[0] + ta[1];
;                 float yp = ty[0] + ty[1];
;                 sa = dpp_add<0xB1>(sa); yp = dpp_add<0xB1>(yp);
;                 sa = dpp_add<0x4E>(sa); yp = dpp_add<0x4E>(yp);
;                 sa = dpp_add<0x124>(sa); yp = dpp_add<0x124>(yp);
;                 sa = dpp_add<0x128>(sa); yp = dpp_add<0x128>(yp);
;                 if (tk > 0) yk[(tk - 1) >> 4] = (cg_ == ((tk - 1) & 15)) ? yp : yk[(tk - 1) >> 4];
;                 S = sa * b4 + T;
;                 rp = r4;
;                 r4 = nr4; d4 = nd4; k4 = nk4; a4 = na4; b4 = nb4; vv = nvv;
	v_pk_mul_f32 v[174:175], v[174:175], v[198:199]
	v_pk_mul_f32 v[26:27], v[26:27], v[198:199]
	v_pk_fma_f32 v[172:173], v[172:173], v[196:197], v[174:175]
	v_pk_fma_f32 v[24:25], v[24:25], v[196:197], v[26:27]
	v_add_f32_e32 v206, v172, v173
	v_pk_mul_f32 v[26:27], v[164:165], v[196:197]
	v_add_f32_e32 v24, v24, v25
	v_add_f32_dpp v25, v206, v206 quad_perm:[1,0,3,2] row_mask:0xf bank_mask:0xf bound_ctrl:1
	v_pk_mul_f32 v[164:165], v[166:167], v[198:199]
	v_add_f32_dpp v24, v24, v24 quad_perm:[1,0,3,2] row_mask:0xf bank_mask:0xf bound_ctrl:1
	v_add_f32_dpp v25, v25, v25 quad_perm:[2,3,0,1] row_mask:0xf bank_mask:0xf bound_ctrl:1
	v_pk_fma_f32 v[164:165], v[170:171], v[202:203], v[164:165] op_sel_hi:[1,0,1]
	v_add_f32_dpp v24, v24, v24 quad_perm:[2,3,0,1] row_mask:0xf bank_mask:0xf bound_ctrl:1
	v_add_f32_dpp v25, v25, v25 row_ror:4 row_mask:0xf bank_mask:0xf bound_ctrl:1
	v_pk_fma_f32 v[26:27], v[168:169], v[202:203], v[26:27] op_sel_hi:[1,0,1]
	v_add_f32_dpp v166, v24, v24 row_ror:4 row_mask:0xf bank_mask:0xf bound_ctrl:1
	v_add_f32_dpp v24, v25, v25 row_ror:8 row_mask:0xf bank_mask:0xf bound_ctrl:1
	v_pk_fma_f32 v[196:197], v[176:177], v[24:25], v[26:27] op_sel_hi:[1,0,1]
	v_add_f32_dpp v25, v166, v166 row_ror:8 row_mask:0xf bank_mask:0xf bound_ctrl:1
	v_cndmask_b32_e64 v31, v31, v25, s[8:9]
	v_pk_fma_f32 v[198:199], v[178:179], v[24:25], v[164:165] op_sel_hi:[1,0,1]
	ds_read_b128 v[24:27], v28 offset:30720
	ds_read_b128 v[164:167], v28 offset:30976
	ds_read_b128 v[168:171], v28 offset:31232
	ds_read_b128 v[172:175], v28 offset:31744
	ds_read_b128 v[176:179], v28 offset:32000
	ds_read_b32 v202, v29 offset:31488
	s_waitcnt lgkmcnt(6)
	v_pk_mul_f32 v[190:191], v[190:191], v[198:199]
	v_pk_mul_f32 v[34:35], v[34:35], v[198:199]
	v_pk_fma_f32 v[188:189], v[188:189], v[196:197], v[190:191]
	v_pk_fma_f32 v[32:33], v[32:33], v[196:197], v[34:35]
	v_add_f32_e32 v206, v188, v189
	v_pk_mul_f32 v[34:35], v[180:181], v[196:197]
	v_add_f32_e32 v32, v32, v33
	v_add_f32_dpp v33, v206, v206 quad_perm:[1,0,3,2] row_mask:0xf bank_mask:0xf bound_ctrl:1
	v_pk_mul_f32 v[180:181], v[182:183], v[198:199]
	v_add_f32_dpp v32, v32, v32 quad_perm:[1,0,3,2] row_mask:0xf bank_mask:0xf bound_ctrl:1
	v_add_f32_dpp v33, v33, v33 quad_perm:[2,3,0,1] row_mask:0xf bank_mask:0xf bound_ctrl:1
	v_pk_fma_f32 v[180:181], v[186:187], v[200:201], v[180:181] op_sel_hi:[1,0,1]
	v_add_f32_dpp v32, v32, v32 quad_perm:[2,3,0,1] row_mask:0xf bank_mask:0xf bound_ctrl:1
	v_add_f32_dpp v33, v33, v33 row_ror:4 row_mask:0xf bank_mask:0xf bound_ctrl:1
	v_pk_fma_f32 v[34:35], v[184:185], v[200:201], v[34:35] op_sel_hi:[1,0,1]
	v_add_f32_dpp v182, v32, v32 row_ror:4 row_mask:0xf bank_mask:0xf bound_ctrl:1
	v_add_f32_dpp v32, v33, v33 row_ror:8 row_mask:0xf bank_mask:0xf bound_ctrl:1
	v_pk_fma_f32 v[196:197], v[192:193], v[32:33], v[34:35] op_sel_hi:[1,0,1]
	v_add_f32_dpp v33, v182, v182 row_ror:8 row_mask:0xf bank_mask:0xf bound_ctrl:1
	v_cndmask_b32_e64 v31, v31, v33, s[10:11]
	v_pk_fma_f32 v[198:199], v[194:195], v[32:33], v[180:181] op_sel_hi:[1,0,1]
	ds_read_b128 v[32:35], v28 offset:32256
	ds_read_b128 v[180:183], v28 offset:32512
	ds_read_b128 v[184:187], v28 offset:32768
	ds_read_b128 v[188:191], v28 offset:33280
	ds_read_b128 v[192:195], v28 offset:33536
	ds_read_b32 v200, v29 offset:33024
	s_waitcnt lgkmcnt(6)
	v_pk_mul_f32 v[174:175], v[174:175], v[198:199]
	v_pk_mul_f32 v[162:163], v[162:163], v[198:199]
	v_pk_fma_f32 v[172:173], v[172:173], v[196:197], v[174:175]
	v_pk_fma_f32 v[160:161], v[160:161], v[196:197], v[162:163]
	v_add_f32_e32 v206, v172, v173
	v_pk_mul_f32 v[162:163], v[164:165], v[196:197]
	v_add_f32_e32 v160, v160, v161
	v_add_f32_dpp v161, v206, v206 quad_perm:[1,0,3,2] row_mask:0xf bank_mask:0xf bound_ctrl:1
	v_pk_mul_f32 v[164:165], v[166:167], v[198:199]
	v_add_f32_dpp v160, v160, v160 quad_perm:[1,0,3,2] row_mask:0xf bank_mask:0xf bound_ctrl:1
	v_add_f32_dpp v161, v161, v161 quad_perm:[2,3,0,1] row_mask:0xf bank_mask:0xf bound_ctrl:1
	v_pk_fma_f32 v[164:165], v[170:171], v[202:203], v[164:165] op_sel_hi:[1,0,1]
	v_add_f32_dpp v160, v160, v160 quad_perm:[2,3,0,1] row_mask:0xf bank_mask:0xf bound_ctrl:1
	v_add_f32_dpp v161, v161, v161 row_ror:4 row_mask:0xf bank_mask:0xf bound_ctrl:1
	v_pk_fma_f32 v[162:163], v[168:169], v[202:203], v[162:163] op_sel_hi:[1,0,1]
	v_add_f32_dpp v166, v160, v160 row_ror:4 row_mask:0xf bank_mask:0xf bound_ctrl:1
	v_add_f32_dpp v160, v161, v161 row_ror:8 row_mask:0xf bank_mask:0xf bound_ctrl:1
	v_pk_fma_f32 v[196:197], v[176:177], v[160:161], v[162:163] op_sel_hi:[1,0,1]
	v_add_f32_dpp v161, v166, v166 row_ror:8 row_mask:0xf bank_mask:0xf bound_ctrl:1
	v_cndmask_b32_e64 v31, v31, v161, s[12:13]
	v_pk_fma_f32 v[198:199], v[178:179], v[160:161], v[164:165] op_sel_hi:[1,0,1]
	ds_read_b128 v[160:163], v28 offset:33792
	ds_read_b128 v[164:167], v28 offset:34048
	ds_read_b128 v[168:171], v28 offset:34304
	ds_read_b128 v[172:175], v28 offset:34816
	ds_read_b128 v[176:179], v28 offset:35072
	ds_read_b32 v202, v29 offset:34560
	s_waitcnt lgkmcnt(6)
; #define LAS __attribute__((address_space(3)))
; __device__ __forceinline__ void rwkv_scan_prompt(const Params& p, LAS unsigned char* lds, int bh, int rq) {
;     ...
;             for (int tk = 0; tk < TC; ++tk) {
;                 f32x4 nr4 = r4, nd4 = d4, nk4 = k4, na4 = a4, nb4 = b4; float nvv = vv;
;                 if (tk < TC - 1) {
;                     const LAS float* o = ob + (tk + 1) * 6 * 64;
;                     nr4 = *(const LAS f32x4*)(o + cg_ * 4); nd4 = *(const LAS f32x4*)(o + 64 + cg_ * 4); nk4 = *(const LAS f32x4*)(o + 128 + cg_ * 4);
;                     na4 = *(const LAS f32x4*)(o + 256 + cg_ * 4); nb4 = *(const LAS f32x4*)(o + 320 + cg_ * 4);
;                     nvv = o[192 + rq * 16 + rloc];
;                 }
;                 __builtin_amdgcn_sched_barrier(0);
;                 typedef float f32x2_ __attribute__((ext_vector_type(2)));
;                 f32x2_ ta = (f32x2_){S[0], S[1]} * (f32x2_){a4[0], a4[1]}; ta = (f32x2_){S[2], S[3]} * (f32x2_){a4[2], a4[3]} + ta;
;                 f32x2_ ty = (f32x2_){S[0], S[1]} * (f32x2_){rp[0], rp[1]}; ty = (f32x2_){S[2], S[3]} * (f32x2_){rp[2], rp[3]} + ty;
;                 const f32x4 T = S * d4 + vv * k4;
;                 float sa = ta[0] + ta[1];
;                 float yp = ty[0] + ty[1];
;                 sa = dpp_add<0xB1>(sa); yp = dpp_add<0xB1>(yp);
;                 sa = dpp_add<0x4E>(sa); yp = dpp_add<0x4E>(yp);
;                 sa = dpp_add<0x124>(sa); yp = dpp_add<0x124>(yp);
;                 sa = dpp_add<0x128>(sa); yp = dpp_add<0x128>(yp);
;                 if (tk > 0) yk[(tk - 1) >> 4] = (cg_ == ((tk - 1) & 15)) ? yp : yk[(tk - 1) >> 4];
;                 S = sa * b4 + T;
;                 rp = r4;
;                 r4 = nr4; d4 = nd4; k4 = nk4; a4 = na4; b4 = nb4; vv = nvv;
	v_pk_mul_f32 v[190:191], v[190:191], v[198:199]
	v_pk_mul_f32 v[26:27], v[26:27], v[198:199]
	v_pk_fma_f32 v[188:189], v[188:189], v[196:197], v[190:191]
	v_pk_fma_f32 v[24:25], v[24:25], v[196:197], v[26:27]
	v_add_f32_e32 v206, v188, v189
	v_pk_mul_f32 v[26:27], v[180:181], v[196:197]
	v_add_f32_e32 v24, v24, v25
	v_add_f32_dpp v25, v206, v206 quad_perm:[1,0,3,2] row_mask:0xf bank_mask:0xf bound_ctrl:1
	v_pk_mul_f32 v[180:181], v[182:183], v[198:199]
	v_add_f32_dpp v24, v24, v24 quad_perm:[1,0,3,2] row_mask:0xf bank_mask:0xf bound_ctrl:1
	v_add_f32_dpp v25, v25, v25 quad_perm:[2,3,0,1] row_mask:0xf bank_mask:0xf bound_ctrl:1
	v_pk_fma_f32 v[180:181], v[186:187], v[200:201], v[180:181] op_sel_hi:[1,0,1]
	v_add_f32_dpp v24, v24, v24 quad_perm:[2,3,0,1] row_mask:0xf bank_mask:0xf bound_ctrl:1
	v_add_f32_dpp v25, v25, v25 row_ror:4 row_mask:0xf bank_mask:0xf bound_ctrl:1
	v_pk_fma_f32 v[26:27], v[184:185], v[200:201], v[26:27] op_sel_hi:[1,0,1]
	v_add_f32_dpp v182, v24, v24 row_ror:4 row_mask:0xf bank_mask:0xf bound_ctrl:1
	v_add_f32_dpp v24, v25, v25 row_ror:8 row_mask:0xf bank_mask:0xf bound_ctrl:1
	v_pk_fma_f32 v[196:197], v[192:193], v[24:25], v[26:27] op_sel_hi:[1,0,1]
	v_add_f32_dpp v25, v182, v182 row_ror:8 row_mask:0xf bank_mask:0xf bound_ctrl:1
	v_cndmask_b32_e64 v31, v31, v25, s[14:15]
	v_pk_fma_f32 v[198:199], v[194:195], v[24:25], v[180:181] op_sel_hi:[1,0,1]
	ds_read_b128 v[24:27], v28 offset:35328
	ds_read_b128 v[180:183], v28 offset:35584
	ds_read_b128 v[184:187], v28 offset:35840
	ds_read_b128 v[188:191], v28 offset:36352
	ds_read_b128 v[192:195], v28 offset:36608
	ds_read_b32 v200, v29 offset:36096
	s_waitcnt lgkmcnt(6)
	v_pk_mul_f32 v[174:175], v[174:175], v[198:199]
	v_pk_mul_f32 v[34:35], v[34:35], v[198:199]
	v_pk_fma_f32 v[172:173], v[172:173], v[196:197], v[174:175]
	v_pk_fma_f32 v[32:33], v[32:33], v[196:197], v[34:35]
	v_add_f32_e32 v206, v172, v173
	v_pk_mul_f32 v[34:35], v[164:165], v[196:197]
	v_add_f32_e32 v32, v32, v33
	v_add_f32_dpp v33, v206, v206 quad_perm:[1,0,3,2] row_mask:0xf bank_mask:0xf bound_ctrl:1
	v_pk_mul_f32 v[164:165], v[166:167], v[198:199]
	v_add_f32_dpp v32, v32, v32 quad_perm:[1,0,3,2] row_mask:0xf bank_mask:0xf bound_ctrl:1
	v_add_f32_dpp v33, v33, v33 quad_perm:[2,3,0,1] row_mask:0xf bank_mask:0xf bound_ctrl:1
	v_pk_fma_f32 v[164:165], v[170:171], v[202:203], v[164:165] op_sel_hi:[1,0,1]
	v_add_f32_dpp v32, v32, v32 quad_perm:[2,3,0,1] row_mask:0xf bank_mask:0xf bound_ctrl:1
	v_add_f32_dpp v33, v33, v33 row_ror:4 row_mask:0xf bank_mask:0xf bound_ctrl:1
	v_pk_fma_f32 v[34:35], v[168:169], v[202:203], v[34:35] op_sel_hi:[1,0,1]
	v_add_f32_dpp v166, v32, v32 row_ror:4 row_mask:0xf bank_mask:0xf bound_ctrl:1
	v_add_f32_dpp v32, v33, v33 row_ror:8 row_mask:0xf bank_mask:0xf bound_ctrl:1
	v_pk_fma_f32 v[196:197], v[176:177], v[32:33], v[34:35] op_sel_hi:[1,0,1]
	v_add_f32_dpp v33, v166, v166 row_ror:8 row_mask:0xf bank_mask:0xf bound_ctrl:1
	v_cndmask_b32_e64 v31, v31, v33, s[16:17]
	v_pk_fma_f32 v[198:199], v[178:179], v[32:33], v[164:165] op_sel_hi:[1,0,1]
	ds_read_b128 v[32:35], v28 offset:36864
	ds_read_b128 v[164:167], v28 offset:37120
	ds_read_b128 v[168:171], v28 offset:37376
	ds_read_b128 v[172:175], v28 offset:37888
	ds_read_b128 v[176:179], v28 offset:38144
	ds_read_b32 v202, v29 offset:37632
	s_waitcnt lgkmcnt(6)
	v_pk_mul_f32 v[190:191], v[190:191], v[198:199]
	v_pk_mul_f32 v[162:163], v[162:163], v[198:199]
	v_pk_fma_f32 v[188:189], v[188:189], v[196:197], v[190:191]
	v_pk_fma_f32 v[160:161], v[160:161], v[196:197], v[162:163]
	v_add_f32_e32 v206, v188, v189
	v_pk_mul_f32 v[162:163], v[180:181], v[196:197]
	v_add_f32_e32 v160, v160, v161
	v_add_f32_dpp v161, v206, v206 quad_perm:[1,0,3,2] row_mask:0xf bank_mask:0xf bound_ctrl:1
	v_pk_mul_f32 v[180:181], v[182:183], v[198:199]
	v_add_f32_dpp v160, v160, v160 quad_perm:[1,0,3,2] row_mask:0xf bank_mask:0xf bound_ctrl:1
	v_add_f32_dpp v161, v161, v161 quad_perm:[2,3,0,1] row_mask:0xf bank_mask:0xf bound_ctrl:1
	v_pk_fma_f32 v[180:181], v[186:187], v[200:201], v[180:181] op_sel_hi:[1,0,1]
	v_add_f32_dpp v160, v160, v160 quad_perm:[2,3,0,1] row_mask:0xf bank_mask:0xf bound_ctrl:1
	v_add_f32_dpp v161, v161, v161 row_ror:4 row_mask:0xf bank_mask:0xf bound_ctrl:1
	v_pk_fma_f32 v[162:163], v[184:185], v[200:201], v[162:163] op_sel_hi:[1,0,1]
	v_add_f32_dpp v182, v160, v160 row_ror:4 row_mask:0xf bank_mask:0xf bound_ctrl:1
	v_add_f32_dpp v160, v161, v161 row_ror:8 row_mask:0xf bank_mask:0xf bound_ctrl:1
	v_pk_fma_f32 v[196:197], v[192:193], v[160:161], v[162:163] op_sel_hi:[1,0,1]
	v_add_f32_dpp v161, v182, v182 row_ror:8 row_mask:0xf bank_mask:0xf bound_ctrl:1
	v_cndmask_b32_e64 v31, v31, v161, s[18:19]
	v_pk_fma_f32 v[198:199], v[194:195], v[160:161], v[180:181] op_sel_hi:[1,0,1]
	ds_read_b128 v[160:163], v28 offset:38400
	ds_read_b128 v[180:183], v28 offset:38656
	ds_read_b128 v[184:187], v28 offset:38912
	ds_read_b128 v[188:191], v28 offset:39424
	ds_read_b128 v[192:195], v28 offset:39680
	ds_read_b32 v200, v29 offset:39168
	s_waitcnt lgkmcnt(6)
; #define LAS __attribute__((address_space(3)))
; __device__ __forceinline__ void rwkv_scan_prompt(const Params& p, LAS unsigned char* lds, int bh, int rq) {
;     ...
;             for (int tk = 0; tk < TC; ++tk) {
;                 f32x4 nr4 = r4, nd4 = d4, nk4 = k4, na4 = a4, nb4 = b4; float nvv = vv;
;                 if (tk < TC - 1) {
;                     const LAS float* o = ob + (tk + 1) * 6 * 64;
;                     nr4 = *(const LAS f32x4*)(o + cg_ * 4); nd4 = *(const LAS f32x4*)(o + 64 + cg_ * 4); nk4 = *(const LAS f32x4*)(o + 128 + cg_ * 4);
;                     na4 = *(const LAS f32x4*)(o + 256 + cg_ * 4); nb4 = *(const LAS f32x4*)(o + 320 + cg_ * 4);
;                     nvv = o[192 + rq * 16 + rloc];
;                 }
;                 __builtin_amdgcn_sched_barrier(0);
;                 typedef float f32x2_ __attribute__((ext_vector_type(2)));
;                 f32x2_ ta = (f32x2_){S[0], S[1]} * (f32x2_){a4[0], a4[1]}; ta = (f32x2_){S[2], S[3]} * (f32x2_){a4[2], a4[3]} + ta;
;                 f32x2_ ty = (f32x2_){S[0], S[1]} * (f32x2_){rp[0], rp[1]}; ty = (f32x2_){S[2], S[3]} * (f32x2_){rp[2], rp[3]} + ty;
;                 const f32x4 T = S * d4 + vv * k4;
;                 float sa = ta[0] + ta[1];
;                 float yp = ty[0] + ty[1];
;                 sa = dpp_add<0xB1>(sa); yp = dpp_add<0xB1>(yp);
;                 sa = dpp_add<0x4E>(sa); yp = dpp_add<0x4E>(yp);
;                 sa = dpp_add<0x124>(sa); yp = dpp_add<0x124>(yp);
;                 sa = dpp_add<0x128>(sa); yp = dpp_add<0x128>(yp);
;                 if (tk > 0) yk[(tk - 1) >> 4] = (cg_ == ((tk - 1) & 15)) ? yp : yk[(tk - 1) >> 4];
;                 S = sa * b4 + T;
;                 rp = r4;
;                 r4 = nr4; d4 = nd4; k4 = nk4; a4 = na4; b4 = nb4; vv = nvv;
	v_pk_mul_f32 v[174:175], v[174:175], v[198:199]
	v_pk_mul_f32 v[26:27], v[26:27], v[198:199]
	v_pk_fma_f32 v[172:173], v[172:173], v[196:197], v[174:175]
	v_pk_fma_f32 v[24:25], v[24:25], v[196:197], v[26:27]
	v_add_f32_e32 v206, v172, v173
	v_pk_mul_f32 v[26:27], v[164:165], v[196:197]
	v_add_f32_e32 v24, v24, v25
	v_add_f32_dpp v25, v206, v206 quad_perm:[1,0,3,2] row_mask:0xf bank_mask:0xf bound_ctrl:1
	v_pk_mul_f32 v[164:165], v[166:167], v[198:199]
	v_add_f32_dpp v24, v24, v24 quad_perm:[1,0,3,2] row_mask:0xf bank_mask:0xf bound_ctrl:1
	v_add_f32_dpp v25, v25, v25 quad_perm:[2,3,0,1] row_mask:0xf bank_mask:0xf bound_ctrl:1
	v_pk_fma_f32 v[164:165], v[170:171], v[202:203], v[164:165] op_sel_hi:[1,0,1]
	v_add_f32_dpp v24, v24, v24 quad_perm:[2,3,0,1] row_mask:0xf bank_mask:0xf bound_ctrl:1
	v_add_f32_dpp v25, v25, v25 row_ror:4 row_mask:0xf bank_mask:0xf bound_ctrl:1
	v_pk_fma_f32 v[26:27], v[168:169], v[202:203], v[26:27] op_sel_hi:[1,0,1]
	v_add_f32_dpp v166, v24, v24 row_ror:4 row_mask:0xf bank_mask:0xf bound_ctrl:1
	v_add_f32_dpp v24, v25, v25 row_ror:8 row_mask:0xf bank_mask:0xf bound_ctrl:1
	v_pk_fma_f32 v[196:197], v[176:177], v[24:25], v[26:27] op_sel_hi:[1,0,1]
	v_add_f32_dpp v25, v166, v166 row_ror:8 row_mask:0xf bank_mask:0xf bound_ctrl:1
	v_cndmask_b32_e64 v31, v31, v25, s[20:21]
	v_pk_fma_f32 v[198:199], v[178:179], v[24:25], v[164:165] op_sel_hi:[1,0,1]
	ds_read_b128 v[24:27], v28 offset:39936
	ds_read_b128 v[164:167], v28 offset:40192
	ds_read_b128 v[168:171], v28 offset:40448
	ds_read_b128 v[172:175], v28 offset:40960
	ds_read_b128 v[176:179], v28 offset:41216
	ds_read_b32 v202, v29 offset:40704
	s_waitcnt lgkmcnt(6)
	v_pk_mul_f32 v[190:191], v[190:191], v[198:199]
	v_pk_mul_f32 v[34:35], v[34:35], v[198:199]
	v_pk_fma_f32 v[188:189], v[188:189], v[196:197], v[190:191]
	v_pk_fma_f32 v[32:33], v[32:33], v[196:197], v[34:35]
	v_add_f32_e32 v206, v188, v189
	v_pk_mul_f32 v[34:35], v[180:181], v[196:197]
	v_add_f32_e32 v32, v32, v33
	v_add_f32_dpp v33, v206, v206 quad_perm:[1,0,3,2] row_mask:0xf bank_mask:0xf bound_ctrl:1
	v_pk_mul_f32 v[180:181], v[182:183], v[198:199]
	v_add_f32_dpp v32, v32, v32 quad_perm:[1,0,3,2] row_mask:0xf bank_mask:0xf bound_ctrl:1
	v_add_f32_dpp v33, v33, v33 quad_perm:[2,3,0,1] row_mask:0xf bank_mask:0xf bound_ctrl:1
	v_pk_fma_f32 v[180:181], v[186:187], v[200:201], v[180:181] op_sel_hi:[1,0,1]
	v_add_f32_dpp v32, v32, v32 quad_perm:[2,3,0,1] row_mask:0xf bank_mask:0xf bound_ctrl:1
	v_add_f32_dpp v33, v33, v33 row_ror:4 row_mask:0xf bank_mask:0xf bound_ctrl:1
	v_pk_fma_f32 v[34:35], v[184:185], v[200:201], v[34:35] op_sel_hi:[1,0,1]
	v_add_f32_dpp v182, v32, v32 row_ror:4 row_mask:0xf bank_mask:0xf bound_ctrl:1
	v_add_f32_dpp v32, v33, v33 row_ror:8 row_mask:0xf bank_mask:0xf bound_ctrl:1
	v_pk_fma_f32 v[196:197], v[192:193], v[32:33], v[34:35] op_sel_hi:[1,0,1]
	v_add_f32_dpp v33, v182, v182 row_ror:8 row_mask:0xf bank_mask:0xf bound_ctrl:1
	v_cndmask_b32_e64 v31, v31, v33, s[22:23]
	v_pk_fma_f32 v[198:199], v[194:195], v[32:33], v[180:181] op_sel_hi:[1,0,1]
	ds_read_b128 v[32:35], v28 offset:41472
	ds_read_b128 v[180:183], v28 offset:41728
	ds_read_b128 v[184:187], v28 offset:41984
	ds_read_b128 v[188:191], v28 offset:42496
	ds_read_b128 v[192:195], v28 offset:42752
	ds_read_b32 v200, v29 offset:42240
	s_waitcnt lgkmcnt(6)
	v_pk_mul_f32 v[174:175], v[174:175], v[198:199]
	v_pk_mul_f32 v[162:163], v[162:163], v[198:199]
	v_pk_fma_f32 v[172:173], v[172:173], v[196:197], v[174:175]
	v_pk_fma_f32 v[160:161], v[160:161], v[196:197], v[162:163]
	v_add_f32_e32 v206, v172, v173
	v_pk_mul_f32 v[162:163], v[164:165], v[196:197]
	v_add_f32_e32 v160, v160, v161
	v_add_f32_dpp v161, v206, v206 quad_perm:[1,0,3,2] row_mask:0xf bank_mask:0xf bound_ctrl:1
	v_pk_mul_f32 v[164:165], v[166:167], v[198:199]
	v_add_f32_dpp v160, v160, v160 quad_perm:[1,0,3,2] row_mask:0xf bank_mask:0xf bound_ctrl:1
	v_add_f32_dpp v161, v161, v161 quad_perm:[2,3,0,1] row_mask:0xf bank_mask:0xf bound_ctrl:1
	v_pk_fma_f32 v[164:165], v[170:171], v[202:203], v[164:165] op_sel_hi:[1,0,1]
	v_add_f32_dpp v160, v160, v160 quad_perm:[2,3,0,1] row_mask:0xf bank_mask:0xf bound_ctrl:1
	v_add_f32_dpp v161, v161, v161 row_ror:4 row_mask:0xf bank_mask:0xf bound_ctrl:1
	v_pk_fma_f32 v[162:163], v[168:169], v[202:203], v[162:163] op_sel_hi:[1,0,1]
	v_add_f32_dpp v166, v160, v160 row_ror:4 row_mask:0xf bank_mask:0xf bound_ctrl:1
	v_add_f32_dpp v160, v161, v161 row_ror:8 row_mask:0xf bank_mask:0xf bound_ctrl:1
	v_pk_fma_f32 v[196:197], v[176:177], v[160:161], v[162:163] op_sel_hi:[1,0,1]
	v_add_f32_dpp v161, v166, v166 row_ror:8 row_mask:0xf bank_mask:0xf bound_ctrl:1
	v_cndmask_b32_e64 v31, v31, v161, s[24:25]
	v_pk_fma_f32 v[198:199], v[178:179], v[160:161], v[164:165] op_sel_hi:[1,0,1]
	ds_read_b128 v[160:163], v28 offset:43008
	ds_read_b128 v[164:167], v28 offset:43264
	ds_read_b128 v[168:171], v28 offset:43520
	ds_read_b128 v[172:175], v28 offset:44032
	ds_read_b128 v[176:179], v28 offset:44288
	ds_read_b32 v202, v29 offset:43776
	s_waitcnt lgkmcnt(6)
; #define LAS __attribute__((address_space(3)))
; __device__ __forceinline__ void rwkv_scan_prompt(const Params& p, LAS unsigned char* lds, int bh, int rq) {
;     ...
;             for (int tk = 0; tk < TC; ++tk) {
;                 f32x4 nr4 = r4, nd4 = d4, nk4 = k4, na4 = a4, nb4 = b4; float nvv = vv;
;                 if (tk < TC - 1) {
;                     const LAS float* o = ob + (tk + 1) * 6 * 64;
;                     nr4 = *(const LAS f32x4*)(o + cg_ * 4); nd4 = *(const LAS f32x4*)(o + 64 + cg_ * 4); nk4 = *(const LAS f32x4*)(o + 128 + cg_ * 4);
;                     na4 = *(const LAS f32x4*)(o + 256 + cg_ * 4); nb4 = *(const LAS f32x4*)(o + 320 + cg_ * 4);
;                     nvv = o[192 + rq * 16 + rloc];
;                 }
;                 __builtin_amdgcn_sched_barrier(0);
;                 typedef float f32x2_ __attribute__((ext_vector_type(2)));
;                 f32x2_ ta = (f32x2_){S[0], S[1]} * (f32x2_){a4[0], a4[1]}; ta = (f32x2_){S[2], S[3]} * (f32x2_){a4[2], a4[3]} + ta;
;                 f32x2_ ty = (f32x2_){S[0], S[1]} * (f32x2_){rp[0], rp[1]}; ty = (f32x2_){S[2], S[3]} * (f32x2_){rp[2], rp[3]} + ty;
;                 const f32x4 T = S * d4 + vv * k4;
;                 float sa = ta[0] + ta[1];
;                 float yp = ty[0] + ty[1];
;                 sa = dpp_add<0xB1>(sa); yp = dpp_add<0xB1>(yp);
;                 sa = dpp_add<0x4E>(sa); yp = dpp_add<0x4E>(yp);
;                 sa = dpp_add<0x124>(sa); yp = dpp_add<0x124>(yp);
;                 sa = dpp_add<0x128>(sa); yp = dpp_add<0x128>(yp);
;                 if (tk > 0) yk[(tk - 1) >> 4] = (cg_ == ((tk - 1) & 15)) ? yp : yk[(tk - 1) >> 4];
;                 S = sa * b4 + T;
;                 rp = r4;
;                 r4 = nr4; d4 = nd4; k4 = nk4; a4 = na4; b4 = nb4; vv = nvv;
	v_pk_mul_f32 v[190:191], v[190:191], v[198:199]
	v_pk_mul_f32 v[26:27], v[26:27], v[198:199]
	v_pk_fma_f32 v[188:189], v[188:189], v[196:197], v[190:191]
	v_pk_fma_f32 v[24:25], v[24:25], v[196:197], v[26:27]
	v_add_f32_e32 v206, v188, v189
	v_pk_mul_f32 v[26:27], v[180:181], v[196:197]
	v_add_f32_e32 v24, v24, v25
	v_add_f32_dpp v25, v206, v206 quad_perm:[1,0,3,2] row_mask:0xf bank_mask:0xf bound_ctrl:1
	v_pk_mul_f32 v[180:181], v[182:183], v[198:199]
	v_add_f32_dpp v24, v24, v24 quad_perm:[1,0,3,2] row_mask:0xf bank_mask:0xf bound_ctrl:1
	v_add_f32_dpp v25, v25, v25 quad_perm:[2,3,0,1] row_mask:0xf bank_mask:0xf bound_ctrl:1
	v_pk_fma_f32 v[180:181], v[186:187], v[200:201], v[180:181] op_sel_hi:[1,0,1]
	v_add_f32_dpp v24, v24, v24 quad_perm:[2,3,0,1] row_mask:0xf bank_mask:0xf bound_ctrl:1
	v_add_f32_dpp v25, v25, v25 row_ror:4 row_mask:0xf bank_mask:0xf bound_ctrl:1
	v_pk_fma_f32 v[26:27], v[184:185], v[200:201], v[26:27] op_sel_hi:[1,0,1]
	v_add_f32_dpp v182, v24, v24 row_ror:4 row_mask:0xf bank_mask:0xf bound_ctrl:1
	v_add_f32_dpp v24, v25, v25 row_ror:8 row_mask:0xf bank_mask:0xf bound_ctrl:1
	v_pk_fma_f32 v[196:197], v[192:193], v[24:25], v[26:27] op_sel_hi:[1,0,1]
	v_add_f32_dpp v25, v182, v182 row_ror:8 row_mask:0xf bank_mask:0xf bound_ctrl:1
	v_cndmask_b32_e64 v31, v31, v25, s[26:27]
	v_pk_fma_f32 v[198:199], v[194:195], v[24:25], v[180:181] op_sel_hi:[1,0,1]
	ds_read_b128 v[24:27], v28 offset:44544
	ds_read_b128 v[180:183], v28 offset:44800
	ds_read_b128 v[184:187], v28 offset:45056
	ds_read_b128 v[188:191], v28 offset:45568
	ds_read_b128 v[192:195], v28 offset:45824
	ds_read_b32 v200, v29 offset:45312
	s_waitcnt lgkmcnt(6)
	v_pk_mul_f32 v[174:175], v[174:175], v[198:199]
	v_pk_mul_f32 v[34:35], v[34:35], v[198:199]
	v_pk_fma_f32 v[172:173], v[172:173], v[196:197], v[174:175]
	v_pk_fma_f32 v[32:33], v[32:33], v[196:197], v[34:35]
	v_add_f32_e32 v206, v172, v173
	v_pk_mul_f32 v[34:35], v[164:165], v[196:197]
	v_add_f32_e32 v32, v32, v33
	v_add_f32_dpp v33, v206, v206 quad_perm:[1,0,3,2] row_mask:0xf bank_mask:0xf bound_ctrl:1
	v_pk_mul_f32 v[164:165], v[166:167], v[198:199]
	v_add_f32_dpp v32, v32, v32 quad_perm:[1,0,3,2] row_mask:0xf bank_mask:0xf bound_ctrl:1
	v_add_f32_dpp v33, v33, v33 quad_perm:[2,3,0,1] row_mask:0xf bank_mask:0xf bound_ctrl:1
	v_pk_fma_f32 v[164:165], v[170:171], v[202:203], v[164:165] op_sel_hi:[1,0,1]
	v_add_f32_dpp v32, v32, v32 quad_perm:[2,3,0,1] row_mask:0xf bank_mask:0xf bound_ctrl:1
	v_add_f32_dpp v33, v33, v33 row_ror:4 row_mask:0xf bank_mask:0xf bound_ctrl:1
	v_pk_fma_f32 v[34:35], v[168:169], v[202:203], v[34:35] op_sel_hi:[1,0,1]
	v_add_f32_dpp v166, v32, v32 row_ror:4 row_mask:0xf bank_mask:0xf bound_ctrl:1
	v_add_f32_dpp v32, v33, v33 row_ror:8 row_mask:0xf bank_mask:0xf bound_ctrl:1
	v_pk_fma_f32 v[196:197], v[176:177], v[32:33], v[34:35] op_sel_hi:[1,0,1]
	v_add_f32_dpp v33, v166, v166 row_ror:8 row_mask:0xf bank_mask:0xf bound_ctrl:1
	v_cndmask_b32_e64 v31, v31, v33, s[28:29]
	v_pk_fma_f32 v[198:199], v[178:179], v[32:33], v[164:165] op_sel_hi:[1,0,1]
	ds_read_b128 v[32:35], v28 offset:46080
	ds_read_b128 v[164:167], v28 offset:46336
	ds_read_b128 v[168:171], v28 offset:46592
	ds_read_b128 v[172:175], v28 offset:47104
	ds_read_b128 v[176:179], v28 offset:47360
	ds_read_b32 v202, v29 offset:46848
	s_waitcnt lgkmcnt(6)
	v_pk_mul_f32 v[190:191], v[190:191], v[198:199]
	v_pk_mul_f32 v[162:163], v[162:163], v[198:199]
	v_pk_fma_f32 v[188:189], v[188:189], v[196:197], v[190:191]
	v_pk_fma_f32 v[160:161], v[160:161], v[196:197], v[162:163]
	v_add_f32_e32 v206, v188, v189
	v_pk_mul_f32 v[162:163], v[180:181], v[196:197]
	v_add_f32_e32 v160, v160, v161
	v_add_f32_dpp v161, v206, v206 quad_perm:[1,0,3,2] row_mask:0xf bank_mask:0xf bound_ctrl:1
	v_pk_mul_f32 v[180:181], v[182:183], v[198:199]
	v_add_f32_dpp v160, v160, v160 quad_perm:[1,0,3,2] row_mask:0xf bank_mask:0xf bound_ctrl:1
	v_add_f32_dpp v161, v161, v161 quad_perm:[2,3,0,1] row_mask:0xf bank_mask:0xf bound_ctrl:1
	v_pk_fma_f32 v[180:181], v[186:187], v[200:201], v[180:181] op_sel_hi:[1,0,1]
	v_add_f32_dpp v160, v160, v160 quad_perm:[2,3,0,1] row_mask:0xf bank_mask:0xf bound_ctrl:1
	v_add_f32_dpp v161, v161, v161 row_ror:4 row_mask:0xf bank_mask:0xf bound_ctrl:1
	v_pk_fma_f32 v[162:163], v[184:185], v[200:201], v[162:163] op_sel_hi:[1,0,1]
	v_add_f32_dpp v182, v160, v160 row_ror:4 row_mask:0xf bank_mask:0xf bound_ctrl:1
	v_add_f32_dpp v160, v161, v161 row_ror:8 row_mask:0xf bank_mask:0xf bound_ctrl:1
	v_pk_fma_f32 v[196:197], v[192:193], v[160:161], v[162:163] op_sel_hi:[1,0,1]
	v_add_f32_dpp v161, v182, v182 row_ror:8 row_mask:0xf bank_mask:0xf bound_ctrl:1
	v_cndmask_b32_e64 v31, v31, v161, s[30:31]
	v_pk_fma_f32 v[198:199], v[194:195], v[160:161], v[180:181] op_sel_hi:[1,0,1]
	ds_read_b128 v[160:163], v28 offset:47616
	ds_read_b128 v[180:183], v28 offset:47872
	ds_read_b128 v[184:187], v28 offset:48128
	ds_read_b128 v[188:191], v28 offset:48640
	ds_read_b128 v[192:195], v28 offset:48896
	ds_read_b32 v28, v29 offset:48384
	s_waitcnt lgkmcnt(6)
; #define LAS __attribute__((address_space(3)))
; __device__ __forceinline__ void rwkv_scan_prompt(const Params& p, LAS unsigned char* lds, int bh, int rq) {
;     ...
;             for (int tk = 0; tk < TC; ++tk) {
;                 f32x4 nr4 = r4, nd4 = d4, nk4 = k4, na4 = a4, nb4 = b4; float nvv = vv;
;                 if (tk < TC - 1) {
;                     const LAS float* o = ob + (tk + 1) * 6 * 64;
;                     nr4 = *(const LAS f32x4*)(o + cg_ * 4); nd4 = *(const LAS f32x4*)(o + 64 + cg_ * 4); nk4 = *(const LAS f32x4*)(o + 128 + cg_ * 4);
;                     na4 = *(const LAS f32x4*)(o + 256 + cg_ * 4); nb4 = *(const LAS f32x4*)(o + 320 + cg_ * 4);
;                     nvv = o[192 + rq * 16 + rloc];
;                 }
;                 __builtin_amdgcn_sched_barrier(0);
;                 typedef float f32x2_ __attribute__((ext_vector_type(2)));
;                 f32x2_ ta = (f32x2_){S[0], S[1]} * (f32x2_){a4[0], a4[1]}; ta = (f32x2_){S[2], S[3]} * (f32x2_){a4[2], a4[3]} + ta;
;                 f32x2_ ty = (f32x2_){S[0], S[1]} * (f32x2_){rp[0], rp[1]}; ty = (f32x2_){S[2], S[3]} * (f32x2_){rp[2], rp[3]} + ty;
;                 const f32x4 T = S * d4 + vv * k4;
;                 float sa = ta[0] + ta[1];
;                 float yp = ty[0] + ty[1];
;                 sa = dpp_add<0xB1>(sa); yp = dpp_add<0xB1>(yp);
;                 sa = dpp_add<0x4E>(sa); yp = dpp_add<0x4E>(yp);
;                 sa = dpp_add<0x124>(sa); yp = dpp_add<0x124>(yp);
;                 sa = dpp_add<0x128>(sa); yp = dpp_add<0x128>(yp);
;                 if (tk > 0) yk[(tk - 1) >> 4] = (cg_ == ((tk - 1) & 15)) ? yp : yk[(tk - 1) >> 4];
;                 S = sa * b4 + T;
;                 rp = r4;
;                 r4 = nr4; d4 = nd4; k4 = nk4; a4 = na4; b4 = nb4; vv = nvv;
;             }
;             {
;                 float yp = S[0] * rp[0] + S[1] * rp[1] + S[2] * rp[2] + S[3] * rp[3];
;                 yp = row_sum16(yp);
;                 yk[(TC - 1) >> 4] = (cg_ == ((TC - 1) & 15)) ? yp : yk[(TC - 1) >> 4];
;             }
; #pragma unroll
;             for (int j = 0; j < TC / 16; ++j) yk[j] += RKB[buf * TC + j * 16 + cg_] * ob[(j * 16 + cg_) * 6 * 64 + 192 + rq * 16 + rloc];
; #pragma unroll
;             for (int j = 0; j < TC / 16; ++j) YRAW[(size_t)(rowbase + c * TC + j * 16 + cg_) * 512 + h * 64 + rq * 16 + rloc] = yk[j];
	v_pk_mul_f32 v[174:175], v[174:175], v[198:199]
	v_pk_mul_f32 v[26:27], v[26:27], v[198:199]
	v_pk_fma_f32 v[172:173], v[172:173], v[196:197], v[174:175]
	v_pk_fma_f32 v[24:25], v[24:25], v[196:197], v[26:27]
	v_add_f32_e32 v29, v172, v173
	v_add_f32_e32 v24, v24, v25
	v_pk_mul_f32 v[26:27], v[164:165], v[196:197]
	v_add_f32_dpp v25, v29, v29 quad_perm:[1,0,3,2] row_mask:0xf bank_mask:0xf bound_ctrl:1
	v_add_f32_dpp v24, v24, v24 quad_perm:[1,0,3,2] row_mask:0xf bank_mask:0xf bound_ctrl:1
	v_pk_mul_f32 v[164:165], v[166:167], v[198:199]
	v_add_f32_dpp v25, v25, v25 quad_perm:[2,3,0,1] row_mask:0xf bank_mask:0xf bound_ctrl:1
	v_add_f32_dpp v24, v24, v24 quad_perm:[2,3,0,1] row_mask:0xf bank_mask:0xf bound_ctrl:1
	v_pk_fma_f32 v[164:165], v[170:171], v[202:203], v[164:165] op_sel_hi:[1,0,1]
	v_add_f32_dpp v25, v25, v25 row_ror:4 row_mask:0xf bank_mask:0xf bound_ctrl:1
	v_add_f32_dpp v29, v24, v24 row_ror:4 row_mask:0xf bank_mask:0xf bound_ctrl:1
	v_pk_fma_f32 v[26:27], v[168:169], v[202:203], v[26:27] op_sel_hi:[1,0,1]
	v_add_f32_dpp v24, v25, v25 row_ror:8 row_mask:0xf bank_mask:0xf bound_ctrl:1
	v_add_f32_dpp v25, v29, v29 row_ror:8 row_mask:0xf bank_mask:0xf bound_ctrl:1
	v_cndmask_b32_e64 v29, v31, v25, s[34:35]
	v_pk_fma_f32 v[26:27], v[176:177], v[24:25], v[26:27] op_sel_hi:[1,0,1]
	v_pk_fma_f32 v[24:25], v[178:179], v[24:25], v[164:165] op_sel_hi:[1,0,1]
	s_waitcnt lgkmcnt(2)
	v_pk_mul_f32 v[164:165], v[190:191], v[24:25]
	v_pk_mul_f32 v[34:35], v[34:35], v[24:25]
	v_pk_fma_f32 v[164:165], v[188:189], v[26:27], v[164:165]
	v_pk_fma_f32 v[32:33], v[32:33], v[26:27], v[34:35]
	v_pk_mul_f32 v[26:27], v[180:181], v[26:27]
	v_pk_mul_f32 v[24:25], v[182:183], v[24:25]
	s_waitcnt lgkmcnt(0)
	v_pk_fma_f32 v[34:35], v[184:185], v[28:29], v[26:27] op_sel_hi:[1,0,1]
	v_add_f32_e32 v26, v164, v165
	v_add_f32_e32 v27, v32, v33
	v_pk_fma_f32 v[24:25], v[186:187], v[28:29], v[24:25] op_sel_hi:[1,0,1]
	v_add_f32_dpp v26, v26, v26 quad_perm:[1,0,3,2] row_mask:0xf bank_mask:0xf bound_ctrl:1
	v_add_f32_dpp v27, v27, v27 quad_perm:[1,0,3,2] row_mask:0xf bank_mask:0xf bound_ctrl:1
	s_lshl_b32 s79, s94, 2
	v_add_f32_dpp v26, v26, v26 quad_perm:[2,3,0,1] row_mask:0xf bank_mask:0xf bound_ctrl:1
	v_add_f32_dpp v27, v27, v27 quad_perm:[2,3,0,1] row_mask:0xf bank_mask:0xf bound_ctrl:1
	s_add_i32 s79, s79, s78
	v_add_f32_dpp v26, v26, v26 row_ror:4 row_mask:0xf bank_mask:0xf bound_ctrl:1
	v_add_f32_dpp v27, v27, v27 row_ror:4 row_mask:0xf bank_mask:0xf bound_ctrl:1
	v_add3_u32 v32, s79, v135, v84
	v_add_f32_dpp v28, v26, v26 row_ror:8 row_mask:0xf bank_mask:0xf bound_ctrl:1
	v_add_f32_dpp v26, v27, v27 row_ror:8 row_mask:0xf bank_mask:0xf bound_ctrl:1
	v_cndmask_b32_e64 v31, v29, v26, s[36:37]
	v_pk_fma_f32 v[26:27], v[194:195], v[28:29], v[24:25] op_sel_hi:[1,0,1]
	v_pk_fma_f32 v[24:25], v[192:193], v[28:29], v[34:35] op_sel_hi:[1,0,1]
	ds_read2st64_b32 v[32:33], v32 offset0:3 offset1:99
	v_mul_f32_e32 v28, v161, v25
	v_fmac_f32_e32 v28, v160, v24
	v_fmac_f32_e32 v28, v162, v26
	v_fmac_f32_e32 v28, v163, v27
	s_nop 1
	v_add_f32_dpp v34, v28, v28 quad_perm:[1,0,3,2] row_mask:0xf bank_mask:0xf bound_ctrl:1
	v_lshl_add_u32 v28, s95, 7, v126
	ds_read2_b32 v[28:29], v28 offset1:16
	v_add_f32_dpp v34, v34, v34 quad_perm:[2,3,0,1] row_mask:0xf bank_mask:0xf bound_ctrl:1
	s_waitcnt lgkmcnt(0)
	v_fmac_f32_e32 v30, v28, v32
	v_add_f32_dpp v34, v34, v34 row_ror:4 row_mask:0xf bank_mask:0xf bound_ctrl:1
	v_add_u32_e32 v28, s0, v159
	s_nop 0
	v_add_f32_dpp v34, v34, v34 row_ror:8 row_mask:0xf bank_mask:0xf bound_ctrl:1
	v_cndmask_b32_e64 v31, v31, v34, s[4:5]
	v_fmac_f32_e32 v31, v29, v33
	v_ashrrev_i32_e32 v29, 31, v28
	v_lshlrev_b64 v[32:33], 11, v[28:29]
	v_add_u32_e32 v28, 16, v28
	v_ashrrev_i32_e32 v29, 31, v28
	v_lshlrev_b64 v[28:29], 11, v[28:29]
	v_lshl_add_u64 v[32:33], v[88:89], 0, v[32:33]
	v_lshl_add_u64 v[28:29], v[88:89], 0, v[28:29]
	global_store_dword v[32:33], v30, off sc0 sc1
	global_store_dword v[28:29], v31, off sc0 sc1
